# on v131: the two per-iteration LDS read-address v_add_u32 of each K-loop hoisted to once per unit (v248/v249)
# speedup vs baseline: 1.0073x; 1.0006x over previous
.LBB0_244:
	s_ashr_i32 s37, s36, 31
	s_lshl_b64 s[38:39], s[36:37], 19
	s_add_u32 s38, s2, s38
	s_addc_u32 s39, s21, s39
	s_and_b64 s[40:41], s[4:5], exec
	s_cselect_b32 s7, s39, s45
	s_cselect_b32 s37, s38, s44
	s_ashr_i32 s25, s24, 31
	s_lshl_b64 s[40:41], s[24:25], 19
	s_add_u32 s40, s8, s40
	s_addc_u32 s41, s9, s41
	s_and_b64 s[48:49], s[4:5], exec
	s_cselect_b32 s25, s41, s47
	s_cselect_b32 s43, s40, s46
	s_add_u32 s44, s44, 0x40080
	s_addc_u32 s45, s45, 0
	s_add_u32 s61, s46, 0x100
	v_mov_b32_e32 v0, 0
	s_addc_u32 s62, s47, 0
	s_mov_b32 s63, -2
	v_mov_b32_e32 v1, v0
	v_mov_b32_e32 v2, v0
	v_mov_b32_e32 v3, v0
	v_mov_b32_e32 v4, v0
	v_mov_b32_e32 v5, v0
	v_mov_b32_e32 v6, v0
	v_mov_b32_e32 v7, v0
	v_mov_b32_e32 v16, v0
	v_mov_b32_e32 v17, v0
	v_mov_b32_e32 v18, v0
	v_mov_b32_e32 v19, v0
	v_mov_b32_e32 v20, v0
	v_mov_b32_e32 v21, v0
	v_mov_b32_e32 v22, v0
	v_mov_b32_e32 v23, v0
	v_mov_b32_e32 v32, v0
	v_mov_b32_e32 v33, v0
	v_mov_b32_e32 v34, v0
	v_mov_b32_e32 v35, v0
	v_mov_b32_e32 v36, v0
	v_mov_b32_e32 v37, v0
	v_mov_b32_e32 v38, v0
	v_mov_b32_e32 v39, v0
	v_mov_b32_e32 v48, v0
	v_mov_b32_e32 v49, v0
	v_mov_b32_e32 v50, v0
	v_mov_b32_e32 v51, v0
	v_mov_b32_e32 v52, v0
	v_mov_b32_e32 v53, v0
	v_mov_b32_e32 v54, v0
	v_mov_b32_e32 v55, v0
	v_mov_b32_e32 v8, v0
	v_mov_b32_e32 v9, v0
	v_mov_b32_e32 v10, v0
	v_mov_b32_e32 v11, v0
	v_mov_b32_e32 v12, v0
	v_mov_b32_e32 v13, v0
	v_mov_b32_e32 v14, v0
	v_mov_b32_e32 v15, v0
	v_mov_b32_e32 v24, v0
	v_mov_b32_e32 v25, v0
	v_mov_b32_e32 v26, v0
	v_mov_b32_e32 v27, v0
	v_mov_b32_e32 v28, v0
	v_mov_b32_e32 v29, v0
	v_mov_b32_e32 v30, v0
	v_mov_b32_e32 v31, v0
	v_mov_b32_e32 v40, v0
	v_mov_b32_e32 v41, v0
	v_mov_b32_e32 v42, v0
	v_mov_b32_e32 v43, v0
	v_mov_b32_e32 v44, v0
	v_mov_b32_e32 v45, v0
	v_mov_b32_e32 v46, v0
	v_mov_b32_e32 v47, v0
	v_mov_b32_e32 v56, v0
	v_mov_b32_e32 v57, v0
	v_mov_b32_e32 v58, v0
	v_mov_b32_e32 v59, v0
	v_mov_b32_e32 v60, v0
	v_mov_b32_e32 v61, v0
	v_mov_b32_e32 v62, v0
	v_mov_b32_e32 v63, v0
	v_mov_b32_e32 v64, v0
	v_mov_b32_e32 v65, v0
	v_mov_b32_e32 v66, v0
	v_mov_b32_e32 v67, v0
	v_mov_b32_e32 v68, v0
	v_mov_b32_e32 v69, v0
	v_mov_b32_e32 v70, v0
	v_mov_b32_e32 v71, v0
	v_mov_b32_e32 v80, v0
	v_mov_b32_e32 v81, v0
	v_mov_b32_e32 v82, v0
	v_mov_b32_e32 v83, v0
	v_mov_b32_e32 v84, v0
	v_mov_b32_e32 v85, v0
	v_mov_b32_e32 v86, v0
	v_mov_b32_e32 v87, v0
	v_mov_b32_e32 v96, v0
	v_mov_b32_e32 v97, v0
	v_mov_b32_e32 v98, v0
	v_mov_b32_e32 v99, v0
	v_mov_b32_e32 v100, v0
	v_mov_b32_e32 v101, v0
	v_mov_b32_e32 v102, v0
	v_mov_b32_e32 v103, v0
	v_mov_b32_e32 v112, v0
	v_mov_b32_e32 v113, v0
	v_mov_b32_e32 v114, v0
	v_mov_b32_e32 v115, v0
	v_mov_b32_e32 v116, v0
	v_mov_b32_e32 v117, v0
	v_mov_b32_e32 v118, v0
	v_mov_b32_e32 v119, v0
	v_mov_b32_e32 v72, v0
	v_mov_b32_e32 v73, v0
	v_mov_b32_e32 v74, v0
	v_mov_b32_e32 v75, v0
	v_mov_b32_e32 v76, v0
	v_mov_b32_e32 v77, v0
	v_mov_b32_e32 v78, v0
	v_mov_b32_e32 v79, v0
	v_mov_b32_e32 v88, v0
	v_mov_b32_e32 v89, v0
	v_mov_b32_e32 v90, v0
	v_mov_b32_e32 v91, v0
	v_mov_b32_e32 v92, v0
	v_mov_b32_e32 v93, v0
	v_mov_b32_e32 v94, v0
	v_mov_b32_e32 v95, v0
	v_mov_b32_e32 v104, v0
	v_mov_b32_e32 v105, v0
	v_mov_b32_e32 v106, v0
	v_mov_b32_e32 v107, v0
	v_mov_b32_e32 v108, v0
	v_mov_b32_e32 v109, v0
	v_mov_b32_e32 v110, v0
	v_mov_b32_e32 v111, v0
	v_mov_b32_e32 v120, v0
	v_mov_b32_e32 v121, v0
	v_mov_b32_e32 v122, v0
	v_mov_b32_e32 v123, v0
	v_mov_b32_e32 v124, v0
	v_mov_b32_e32 v125, v0
	v_mov_b32_e32 v126, v0
	v_mov_b32_e32 v127, v0
	v_add_u32_e32 v248, 0x18000, v176
	v_add_u32_e32 v249, 0x1c000, v176
.LBB0_245:
	ds_read_b128 v[144:147], v178
	ds_read_b128 v[148:151], v178 offset:1024
	ds_read_b128 v[152:155], v178 offset:2048
	ds_read_b128 v[156:159], v178 offset:3072
	ds_read_b128 v[160:163], v179
	ds_read_b128 v[164:167], v179 offset:1024
	ds_read_b128 v[168:171], v179 offset:2048
	ds_read_b128 v[182:185], v179 offset:3072
	s_add_u32 s46, s44, 0xfffc0080
	s_addc_u32 s47, s45, -1
	s_cmp_eq_u32 s63, 12
	s_cselect_b32 s49, s7, s47
	s_cselect_b32 s48, s37, s46
	s_cselect_b32 s47, s25, s62
	s_cselect_b32 s46, s43, s61
	s_add_i32 m0, s31, 0xc000
	ds_read_b128 v[186:189], v180
	ds_read_b128 v[190:193], v180 offset:1024
	ds_read_b128 v[194:197], v180 offset:2048
	ds_read_b128 v[198:201], v180 offset:3072
	ds_read_b128 v[202:205], v180 offset:4096
	ds_read_b128 v[210:213], v180 offset:5120
	ds_read_b128 v[214:217], v180 offset:6144
	ds_read_b128 v[218:221], v180 offset:7168
	global_load_lds_dwordx4 v136, s[44:45]
	s_add_i32 m0, s31, 0xe000
	s_nop 0
	global_load_lds_dwordx4 v138, s[44:45]
	s_waitcnt vmcnt(8)
	s_waitcnt lgkmcnt(0)
	s_barrier
	s_setprio 1
	s_waitcnt lgkmcnt(0)
	v_mfma_f32_16x16x32_bf16 v[124:127], v[144:147], v[186:189], v[124:127]
	v_mfma_f32_16x16x32_bf16 v[120:123], v[152:155], v[186:189], v[120:123]
	v_mfma_f32_16x16x32_bf16 v[108:111], v[144:147], v[194:197], v[108:111]
	v_mfma_f32_16x16x32_bf16 v[104:107], v[152:155], v[194:197], v[104:107]
	v_mfma_f32_16x16x32_bf16 v[92:95], v[144:147], v[202:205], v[92:95]
	v_mfma_f32_16x16x32_bf16 v[88:91], v[152:155], v[202:205], v[88:91]
	v_mfma_f32_16x16x32_bf16 v[76:79], v[144:147], v[214:217], v[76:79]
	v_mfma_f32_16x16x32_bf16 v[72:75], v[152:155], v[214:217], v[72:75]
	v_mfma_f32_16x16x32_bf16 v[124:127], v[148:151], v[190:193], v[124:127]
	v_mfma_f32_16x16x32_bf16 v[120:123], v[156:159], v[190:193], v[120:123]
	v_mfma_f32_16x16x32_bf16 v[108:111], v[148:151], v[198:201], v[108:111]
	v_mfma_f32_16x16x32_bf16 v[104:107], v[156:159], v[198:201], v[104:107]
	v_mfma_f32_16x16x32_bf16 v[92:95], v[148:151], v[210:213], v[92:95]
	v_mfma_f32_16x16x32_bf16 v[88:91], v[156:159], v[210:213], v[88:91]
	v_mfma_f32_16x16x32_bf16 v[76:79], v[148:151], v[218:221], v[76:79]
	v_mfma_f32_16x16x32_bf16 v[72:75], v[156:159], v[218:221], v[72:75]
	v_mfma_f32_16x16x32_bf16 v[116:119], v[160:163], v[186:189], v[116:119]
	v_mfma_f32_16x16x32_bf16 v[112:115], v[168:171], v[186:189], v[112:115]
	v_mfma_f32_16x16x32_bf16 v[100:103], v[160:163], v[194:197], v[100:103]
	v_mfma_f32_16x16x32_bf16 v[96:99], v[168:171], v[194:197], v[96:99]
	v_mfma_f32_16x16x32_bf16 v[84:87], v[160:163], v[202:205], v[84:87]
	v_mfma_f32_16x16x32_bf16 v[80:83], v[168:171], v[202:205], v[80:83]
	v_mfma_f32_16x16x32_bf16 v[68:71], v[160:163], v[214:217], v[68:71]
	v_mfma_f32_16x16x32_bf16 v[64:67], v[168:171], v[214:217], v[64:67]
	v_mfma_f32_16x16x32_bf16 v[116:119], v[164:167], v[190:193], v[116:119]
	v_mfma_f32_16x16x32_bf16 v[112:115], v[182:185], v[190:193], v[112:115]
	v_mfma_f32_16x16x32_bf16 v[100:103], v[164:167], v[198:201], v[100:103]
	v_mfma_f32_16x16x32_bf16 v[96:99], v[182:185], v[198:201], v[96:99]
	v_mfma_f32_16x16x32_bf16 v[84:87], v[164:167], v[210:213], v[84:87]
	v_mfma_f32_16x16x32_bf16 v[80:83], v[182:185], v[210:213], v[80:83]
	v_mfma_f32_16x16x32_bf16 v[68:71], v[164:167], v[218:221], v[68:71]
	v_mfma_f32_16x16x32_bf16 v[64:67], v[182:185], v[218:221], v[64:67]
	s_setprio 0
	s_barrier
	s_add_u32 s98, s46, s16
	s_addc_u32 s99, s47, s17
	s_add_u32 s100, s48, s16
	s_addc_u32 s101, s49, s17
	s_add_i32 s64, s35, s23
	s_mov_b32 m0, s64
	ds_read_b128 v[186:189], v180 offset:16384
	ds_read_b128 v[190:193], v180 offset:17408
	ds_read_b128 v[194:197], v180 offset:18432
	ds_read_b128 v[198:201], v180 offset:19456
	ds_read_b128 v[202:205], v180 offset:20480
	ds_read_b128 v[210:213], v180 offset:21504
	ds_read_b128 v[214:217], v180 offset:22528
	ds_read_b128 v[218:221], v180 offset:23552
	global_load_lds_dwordx4 v130, s[46:47]
	s_add_i32 m0, s64, 0x2000
	s_add_u32 s64, s46, 0x40000
	s_addc_u32 s65, s47, 0
	s_add_i32 s66, s59, s23
	global_load_lds_dwordx4 v134, s[46:47]
	s_mov_b32 m0, s66
	s_nop 0
	global_load_lds_dwordx4 v130, s[64:65]
	s_add_i32 m0, s66, 0x2000
	s_nop 0
	global_load_lds_dwordx4 v134, s[64:65]
	s_mov_b32 m0, s31
	s_nop 0
	global_load_lds_dwordx4 v128, s[48:49]
	s_mov_b32 m0, s50
	s_nop 0
	global_load_lds_dwordx4 v132, s[48:49]
	s_waitcnt vmcnt(8)
	s_waitcnt lgkmcnt(0)
	s_barrier
	s_setprio 1
	s_waitcnt lgkmcnt(0)
	v_mfma_f32_16x16x32_bf16 v[60:63], v[144:147], v[186:189], v[60:63]
	v_mfma_f32_16x16x32_bf16 v[56:59], v[152:155], v[186:189], v[56:59]
	v_mfma_f32_16x16x32_bf16 v[44:47], v[144:147], v[194:197], v[44:47]
	v_mfma_f32_16x16x32_bf16 v[40:43], v[152:155], v[194:197], v[40:43]
	v_mfma_f32_16x16x32_bf16 v[28:31], v[144:147], v[202:205], v[28:31]
	v_mfma_f32_16x16x32_bf16 v[24:27], v[152:155], v[202:205], v[24:27]
	v_mfma_f32_16x16x32_bf16 v[12:15], v[144:147], v[214:217], v[12:15]
	v_mfma_f32_16x16x32_bf16 v[8:11], v[152:155], v[214:217], v[8:11]
	v_mfma_f32_16x16x32_bf16 v[60:63], v[148:151], v[190:193], v[60:63]
	v_mfma_f32_16x16x32_bf16 v[56:59], v[156:159], v[190:193], v[56:59]
	v_mfma_f32_16x16x32_bf16 v[44:47], v[148:151], v[198:201], v[44:47]
	v_mfma_f32_16x16x32_bf16 v[40:43], v[156:159], v[198:201], v[40:43]
	v_mfma_f32_16x16x32_bf16 v[28:31], v[148:151], v[210:213], v[28:31]
	v_mfma_f32_16x16x32_bf16 v[24:27], v[156:159], v[210:213], v[24:27]
	v_mfma_f32_16x16x32_bf16 v[12:15], v[148:151], v[218:221], v[12:15]
	v_mfma_f32_16x16x32_bf16 v[8:11], v[156:159], v[218:221], v[8:11]
	v_mfma_f32_16x16x32_bf16 v[52:55], v[160:163], v[186:189], v[52:55]
	v_mfma_f32_16x16x32_bf16 v[48:51], v[168:171], v[186:189], v[48:51]
	v_mfma_f32_16x16x32_bf16 v[36:39], v[160:163], v[194:197], v[36:39]
	v_mfma_f32_16x16x32_bf16 v[32:35], v[168:171], v[194:197], v[32:35]
	v_mfma_f32_16x16x32_bf16 v[20:23], v[160:163], v[202:205], v[20:23]
	v_mfma_f32_16x16x32_bf16 v[16:19], v[168:171], v[202:205], v[16:19]
	v_mfma_f32_16x16x32_bf16 v[4:7], v[160:163], v[214:217], v[4:7]
	v_mfma_f32_16x16x32_bf16 v[0:3], v[168:171], v[214:217], v[0:3]
	v_mfma_f32_16x16x32_bf16 v[52:55], v[164:167], v[190:193], v[52:55]
	v_mfma_f32_16x16x32_bf16 v[48:51], v[182:185], v[190:193], v[48:51]
	v_mfma_f32_16x16x32_bf16 v[36:39], v[164:167], v[198:201], v[36:39]
	v_mfma_f32_16x16x32_bf16 v[32:35], v[182:185], v[198:201], v[32:35]
	v_mfma_f32_16x16x32_bf16 v[20:23], v[164:167], v[210:213], v[20:23]
	v_mfma_f32_16x16x32_bf16 v[16:19], v[182:185], v[210:213], v[16:19]
	v_mfma_f32_16x16x32_bf16 v[4:7], v[164:167], v[218:221], v[4:7]
	v_mfma_f32_16x16x32_bf16 v[0:3], v[182:185], v[218:221], v[0:3]
	s_setprio 0
	s_barrier
	s_add_i32 s64, 0, 0x18000
	s_add_i32 s65, 0, 0x1c000
	ds_read_b128 v[144:147], v248
	ds_read_b128 v[148:151], v248 offset:1024
	ds_read_b128 v[152:155], v248 offset:2048
	ds_read_b128 v[156:159], v248 offset:3072
	ds_read_b128 v[160:163], v249
	ds_read_b128 v[164:167], v249 offset:1024
	ds_read_b128 v[168:171], v249 offset:2048
	ds_read_b128 v[182:185], v249 offset:3072
	s_add_u32 s48, s48, 0x40000
	s_addc_u32 s49, s49, 0
	s_mov_b32 m0, s51
	ds_read_b128 v[186:189], v180 offset:32768
	ds_read_b128 v[190:193], v180 offset:33792
	ds_read_b128 v[194:197], v180 offset:34816
	ds_read_b128 v[198:201], v180 offset:35840
	ds_read_b128 v[202:205], v180 offset:36864
	ds_read_b128 v[210:213], v180 offset:37888
	ds_read_b128 v[214:217], v180 offset:38912
	ds_read_b128 v[218:221], v180 offset:39936
	global_load_lds_dwordx4 v128, s[48:49]
	s_mov_b32 m0, s52
	s_nop 0
	global_load_lds_dwordx4 v132, s[48:49]
	s_waitcnt vmcnt(8)
	s_waitcnt lgkmcnt(0)
	s_barrier
	s_setprio 1
	s_waitcnt lgkmcnt(0)
	v_mfma_f32_16x16x32_bf16 v[124:127], v[144:147], v[186:189], v[124:127]
	v_mfma_f32_16x16x32_bf16 v[120:123], v[152:155], v[186:189], v[120:123]
	v_mfma_f32_16x16x32_bf16 v[108:111], v[144:147], v[194:197], v[108:111]
	v_mfma_f32_16x16x32_bf16 v[104:107], v[152:155], v[194:197], v[104:107]
	v_mfma_f32_16x16x32_bf16 v[92:95], v[144:147], v[202:205], v[92:95]
	v_mfma_f32_16x16x32_bf16 v[88:91], v[152:155], v[202:205], v[88:91]
	v_mfma_f32_16x16x32_bf16 v[76:79], v[144:147], v[214:217], v[76:79]
	v_mfma_f32_16x16x32_bf16 v[72:75], v[152:155], v[214:217], v[72:75]
	v_mfma_f32_16x16x32_bf16 v[124:127], v[148:151], v[190:193], v[124:127]
	v_mfma_f32_16x16x32_bf16 v[120:123], v[156:159], v[190:193], v[120:123]
	v_mfma_f32_16x16x32_bf16 v[108:111], v[148:151], v[198:201], v[108:111]
	v_mfma_f32_16x16x32_bf16 v[104:107], v[156:159], v[198:201], v[104:107]
	v_mfma_f32_16x16x32_bf16 v[92:95], v[148:151], v[210:213], v[92:95]
	v_mfma_f32_16x16x32_bf16 v[88:91], v[156:159], v[210:213], v[88:91]
	v_mfma_f32_16x16x32_bf16 v[76:79], v[148:151], v[218:221], v[76:79]
	v_mfma_f32_16x16x32_bf16 v[72:75], v[156:159], v[218:221], v[72:75]
	v_mfma_f32_16x16x32_bf16 v[116:119], v[160:163], v[186:189], v[116:119]
	v_mfma_f32_16x16x32_bf16 v[112:115], v[168:171], v[186:189], v[112:115]
	v_mfma_f32_16x16x32_bf16 v[100:103], v[160:163], v[194:197], v[100:103]
	v_mfma_f32_16x16x32_bf16 v[96:99], v[168:171], v[194:197], v[96:99]
	v_mfma_f32_16x16x32_bf16 v[84:87], v[160:163], v[202:205], v[84:87]
	v_mfma_f32_16x16x32_bf16 v[80:83], v[168:171], v[202:205], v[80:83]
	v_mfma_f32_16x16x32_bf16 v[68:71], v[160:163], v[214:217], v[68:71]
	v_mfma_f32_16x16x32_bf16 v[64:67], v[168:171], v[214:217], v[64:67]
	v_mfma_f32_16x16x32_bf16 v[116:119], v[164:167], v[190:193], v[116:119]
	v_mfma_f32_16x16x32_bf16 v[112:115], v[182:185], v[190:193], v[112:115]
	v_mfma_f32_16x16x32_bf16 v[100:103], v[164:167], v[198:201], v[100:103]
	v_mfma_f32_16x16x32_bf16 v[96:99], v[182:185], v[198:201], v[96:99]
	v_mfma_f32_16x16x32_bf16 v[84:87], v[164:167], v[210:213], v[84:87]
	v_mfma_f32_16x16x32_bf16 v[80:83], v[182:185], v[210:213], v[80:83]
	v_mfma_f32_16x16x32_bf16 v[68:71], v[164:167], v[218:221], v[68:71]
	v_mfma_f32_16x16x32_bf16 v[64:67], v[182:185], v[218:221], v[64:67]
	s_setprio 0
	s_barrier
	s_add_i32 s48, s64, s23
	s_mov_b32 m0, s48
	ds_read_b128 v[186:189], v180 offset:49152
	ds_read_b128 v[190:193], v180 offset:50176
	ds_read_b128 v[194:197], v180 offset:51200
	ds_read_b128 v[198:201], v180 offset:52224
	ds_read_b128 v[202:205], v180 offset:53248
	ds_read_b128 v[210:213], v180 offset:54272
	ds_read_b128 v[214:217], v180 offset:55296
	ds_read_b128 v[218:221], v180 offset:56320
	global_load_lds_dwordx4 v130, s[98:99]
	s_add_i32 m0, s48, 0x2000
	s_add_u32 s46, s46, 0x40080
	s_addc_u32 s47, s47, 0
	s_add_i32 s48, s65, s23
	global_load_lds_dwordx4 v134, s[98:99]
	s_mov_b32 m0, s48
	s_nop 0
	global_load_lds_dwordx4 v130, s[46:47]
	s_add_i32 m0, s48, 0x2000
	s_nop 0
	global_load_lds_dwordx4 v134, s[46:47]
	s_mov_b32 m0, s54
	s_nop 0
	global_load_lds_dwordx4 v128, s[100:101]
	s_mov_b32 m0, s55
	s_nop 0
	global_load_lds_dwordx4 v132, s[100:101]
	s_waitcnt vmcnt(8)
	s_waitcnt lgkmcnt(0)
	s_barrier
	s_setprio 1
	s_waitcnt lgkmcnt(0)
	v_mfma_f32_16x16x32_bf16 v[60:63], v[144:147], v[186:189], v[60:63]
	v_mfma_f32_16x16x32_bf16 v[56:59], v[152:155], v[186:189], v[56:59]
	v_mfma_f32_16x16x32_bf16 v[44:47], v[144:147], v[194:197], v[44:47]
	v_mfma_f32_16x16x32_bf16 v[40:43], v[152:155], v[194:197], v[40:43]
	v_mfma_f32_16x16x32_bf16 v[28:31], v[144:147], v[202:205], v[28:31]
	v_mfma_f32_16x16x32_bf16 v[24:27], v[152:155], v[202:205], v[24:27]
	v_mfma_f32_16x16x32_bf16 v[12:15], v[144:147], v[214:217], v[12:15]
	v_mfma_f32_16x16x32_bf16 v[8:11], v[152:155], v[214:217], v[8:11]
	v_mfma_f32_16x16x32_bf16 v[60:63], v[148:151], v[190:193], v[60:63]
	v_mfma_f32_16x16x32_bf16 v[56:59], v[156:159], v[190:193], v[56:59]
	v_mfma_f32_16x16x32_bf16 v[44:47], v[148:151], v[198:201], v[44:47]
	v_mfma_f32_16x16x32_bf16 v[40:43], v[156:159], v[198:201], v[40:43]
	v_mfma_f32_16x16x32_bf16 v[28:31], v[148:151], v[210:213], v[28:31]
	v_mfma_f32_16x16x32_bf16 v[24:27], v[156:159], v[210:213], v[24:27]
	v_mfma_f32_16x16x32_bf16 v[12:15], v[148:151], v[218:221], v[12:15]
	v_mfma_f32_16x16x32_bf16 v[8:11], v[156:159], v[218:221], v[8:11]
	v_mfma_f32_16x16x32_bf16 v[52:55], v[160:163], v[186:189], v[52:55]
	v_mfma_f32_16x16x32_bf16 v[48:51], v[168:171], v[186:189], v[48:51]
	v_mfma_f32_16x16x32_bf16 v[36:39], v[160:163], v[194:197], v[36:39]
	v_mfma_f32_16x16x32_bf16 v[32:35], v[168:171], v[194:197], v[32:35]
	v_mfma_f32_16x16x32_bf16 v[20:23], v[160:163], v[202:205], v[20:23]
	v_mfma_f32_16x16x32_bf16 v[16:19], v[168:171], v[202:205], v[16:19]
	v_mfma_f32_16x16x32_bf16 v[4:7], v[160:163], v[214:217], v[4:7]
	v_mfma_f32_16x16x32_bf16 v[0:3], v[168:171], v[214:217], v[0:3]
	v_mfma_f32_16x16x32_bf16 v[52:55], v[164:167], v[190:193], v[52:55]
	v_mfma_f32_16x16x32_bf16 v[48:51], v[182:185], v[190:193], v[48:51]
	v_mfma_f32_16x16x32_bf16 v[36:39], v[164:167], v[198:201], v[36:39]
	v_mfma_f32_16x16x32_bf16 v[32:35], v[182:185], v[198:201], v[32:35]
	v_mfma_f32_16x16x32_bf16 v[20:23], v[164:167], v[210:213], v[20:23]
	v_mfma_f32_16x16x32_bf16 v[16:19], v[182:185], v[210:213], v[16:19]
	v_mfma_f32_16x16x32_bf16 v[4:7], v[164:167], v[218:221], v[4:7]
	v_mfma_f32_16x16x32_bf16 v[0:3], v[182:185], v[218:221], v[0:3]
	s_setprio 0
	s_barrier
	s_add_i32 s63, s63, 2
	s_add_u32 s44, s44, 0x100
	s_addc_u32 s45, s45, 0
	s_add_u32 s61, s61, 0x100
	s_addc_u32 s62, s62, 0
	s_cmp_gt_u32 s63, 13
	s_cbranch_scc0 .LBB0_245
	s_and_b64 vcc, exec, s[18:19]
	s_cbranch_vccz .LBB0_248
	s_barrier

.LBB0_491:
	s_ashr_i32 s37, s36, 31
	s_lshl_b64 s[38:39], s[36:37], 19
	s_add_u32 s38, s2, s38
	s_addc_u32 s39, s31, s39
	s_and_b64 s[40:41], s[8:9], exec
	s_cselect_b32 s37, s39, s47
	s_cselect_b32 s43, s38, s46
	s_ashr_i32 s25, s24, 31
	s_lshl_b64 s[40:41], s[24:25], 19
	s_add_u32 s40, s34, s40
	s_addc_u32 s41, s35, s41
	s_and_b64 s[50:51], s[8:9], exec
	s_cselect_b32 s25, s41, s49
	s_cselect_b32 s63, s40, s48
	s_add_u32 s46, s46, 0x40080
	s_addc_u32 s47, s47, 0
	s_add_u32 s64, s48, 0x100
	v_mov_b32_e32 v0, 0
	s_addc_u32 s65, s49, 0
	s_mov_b32 s66, -2
	s_waitcnt lgkmcnt(0)
	v_mov_b32_e32 v1, v0
	v_mov_b32_e32 v2, v0
	v_mov_b32_e32 v3, v0
	v_mov_b32_e32 v4, v0
	v_mov_b32_e32 v5, v0
	v_mov_b32_e32 v6, v0
	v_mov_b32_e32 v7, v0
	v_mov_b32_e32 v16, v0
	v_mov_b32_e32 v17, v0
	v_mov_b32_e32 v18, v0
	v_mov_b32_e32 v19, v0
	v_mov_b32_e32 v20, v0
	v_mov_b32_e32 v21, v0
	v_mov_b32_e32 v22, v0
	v_mov_b32_e32 v23, v0
	v_mov_b32_e32 v32, v0
	v_mov_b32_e32 v33, v0
	v_mov_b32_e32 v34, v0
	v_mov_b32_e32 v35, v0
	v_mov_b32_e32 v36, v0
	v_mov_b32_e32 v37, v0
	v_mov_b32_e32 v38, v0
	v_mov_b32_e32 v39, v0
	v_mov_b32_e32 v48, v0
	v_mov_b32_e32 v49, v0
	v_mov_b32_e32 v50, v0
	v_mov_b32_e32 v51, v0
	v_mov_b32_e32 v52, v0
	v_mov_b32_e32 v53, v0
	v_mov_b32_e32 v54, v0
	v_mov_b32_e32 v55, v0
	v_mov_b32_e32 v8, v0
	v_mov_b32_e32 v9, v0
	v_mov_b32_e32 v10, v0
	v_mov_b32_e32 v11, v0
	v_mov_b32_e32 v12, v0
	v_mov_b32_e32 v13, v0
	v_mov_b32_e32 v14, v0
	v_mov_b32_e32 v15, v0
	v_mov_b32_e32 v24, v0
	v_mov_b32_e32 v25, v0
	v_mov_b32_e32 v26, v0
	v_mov_b32_e32 v27, v0
	v_mov_b32_e32 v28, v0
	v_mov_b32_e32 v29, v0
	v_mov_b32_e32 v30, v0
	v_mov_b32_e32 v31, v0
	v_mov_b32_e32 v40, v0
	v_mov_b32_e32 v41, v0
	v_mov_b32_e32 v42, v0
	v_mov_b32_e32 v43, v0
	v_mov_b32_e32 v44, v0
	v_mov_b32_e32 v45, v0
	v_mov_b32_e32 v46, v0
	v_mov_b32_e32 v47, v0
	v_mov_b32_e32 v56, v0
	v_mov_b32_e32 v57, v0
	v_mov_b32_e32 v58, v0
	v_mov_b32_e32 v59, v0
	v_mov_b32_e32 v60, v0
	v_mov_b32_e32 v61, v0
	v_mov_b32_e32 v62, v0
	v_mov_b32_e32 v63, v0
	v_mov_b32_e32 v64, v0
	v_mov_b32_e32 v65, v0
	v_mov_b32_e32 v66, v0
	v_mov_b32_e32 v67, v0
	v_mov_b32_e32 v68, v0
	v_mov_b32_e32 v69, v0
	v_mov_b32_e32 v70, v0
	v_mov_b32_e32 v71, v0
	v_mov_b32_e32 v80, v0
	v_mov_b32_e32 v81, v0
	v_mov_b32_e32 v82, v0
	v_mov_b32_e32 v83, v0
	v_mov_b32_e32 v84, v0
	v_mov_b32_e32 v85, v0
	v_mov_b32_e32 v86, v0
	v_mov_b32_e32 v87, v0
	v_mov_b32_e32 v96, v0
	v_mov_b32_e32 v97, v0
	v_mov_b32_e32 v98, v0
	v_mov_b32_e32 v99, v0
	v_mov_b32_e32 v100, v0
	v_mov_b32_e32 v101, v0
	v_mov_b32_e32 v102, v0
	v_mov_b32_e32 v103, v0
	v_mov_b32_e32 v112, v0
	v_mov_b32_e32 v113, v0
	v_mov_b32_e32 v114, v0
	v_mov_b32_e32 v115, v0
	v_mov_b32_e32 v116, v0
	v_mov_b32_e32 v117, v0
	v_mov_b32_e32 v118, v0
	v_mov_b32_e32 v119, v0
	v_mov_b32_e32 v72, v0
	v_mov_b32_e32 v73, v0
	v_mov_b32_e32 v74, v0
	v_mov_b32_e32 v75, v0
	v_mov_b32_e32 v76, v0
	v_mov_b32_e32 v77, v0
	v_mov_b32_e32 v78, v0
	v_mov_b32_e32 v79, v0
	v_mov_b32_e32 v88, v0
	v_mov_b32_e32 v89, v0
	v_mov_b32_e32 v90, v0
	v_mov_b32_e32 v91, v0
	v_mov_b32_e32 v92, v0
	v_mov_b32_e32 v93, v0
	v_mov_b32_e32 v94, v0
	v_mov_b32_e32 v95, v0
	v_mov_b32_e32 v104, v0
	v_mov_b32_e32 v105, v0
	v_mov_b32_e32 v106, v0
	v_mov_b32_e32 v107, v0
	v_mov_b32_e32 v108, v0
	v_mov_b32_e32 v109, v0
	v_mov_b32_e32 v110, v0
	v_mov_b32_e32 v111, v0
	v_mov_b32_e32 v120, v0
	v_mov_b32_e32 v121, v0
	v_mov_b32_e32 v122, v0
	v_mov_b32_e32 v123, v0
	v_mov_b32_e32 v124, v0
	v_mov_b32_e32 v125, v0
	v_mov_b32_e32 v126, v0
	v_mov_b32_e32 v127, v0
	v_add_u32_e32 v248, 0x18000, v173
	v_add_u32_e32 v249, 0x1c000, v173
.LBB0_492:
	ds_read_b128 v[128:131], v179
	ds_read_b128 v[132:135], v179 offset:1024
	ds_read_b128 v[136:139], v179 offset:2048
	ds_read_b128 v[140:143], v179 offset:3072
	ds_read_b128 v[144:147], v187
	ds_read_b128 v[148:151], v187 offset:1024
	ds_read_b128 v[180:183], v187 offset:2048
	ds_read_b128 v[188:191], v187 offset:3072
	s_add_u32 s48, s46, 0xfffc0080
	s_addc_u32 s49, s47, -1
	s_cmp_eq_u32 s66, 12
	s_cselect_b32 s51, s37, s49
	s_cselect_b32 s50, s43, s48
	s_cselect_b32 s49, s25, s65
	s_cselect_b32 s48, s63, s64
	s_add_i32 m0, s45, 0xc000
	ds_read_b128 v[196:199], v195
	ds_read_b128 v[202:205], v195 offset:1024
	ds_read_b128 v[210:213], v195 offset:2048
	ds_read_b128 v[214:217], v195 offset:3072
	ds_read_b128 v[218:221], v195 offset:4096
	ds_read_b128 v[222:225], v195 offset:5120
	ds_read_b128 v[226:229], v195 offset:6144
	ds_read_b128 v[230:233], v195 offset:7168
	global_load_lds_dwordx4 v160, s[46:47]
	s_add_i32 m0, s45, 0xe000
	s_nop 0
	global_load_lds_dwordx4 v162, s[46:47]
	s_waitcnt vmcnt(8)
	s_waitcnt lgkmcnt(0)
	s_barrier
	s_setprio 1
	s_waitcnt lgkmcnt(0)
	v_mfma_f32_16x16x32_bf16 v[124:127], v[128:131], v[196:199], v[124:127]
	v_mfma_f32_16x16x32_bf16 v[120:123], v[136:139], v[196:199], v[120:123]
	v_mfma_f32_16x16x32_bf16 v[108:111], v[128:131], v[210:213], v[108:111]
	v_mfma_f32_16x16x32_bf16 v[104:107], v[136:139], v[210:213], v[104:107]
	v_mfma_f32_16x16x32_bf16 v[92:95], v[128:131], v[218:221], v[92:95]
	v_mfma_f32_16x16x32_bf16 v[88:91], v[136:139], v[218:221], v[88:91]
	v_mfma_f32_16x16x32_bf16 v[76:79], v[128:131], v[226:229], v[76:79]
	v_mfma_f32_16x16x32_bf16 v[72:75], v[136:139], v[226:229], v[72:75]
	v_mfma_f32_16x16x32_bf16 v[124:127], v[132:135], v[202:205], v[124:127]
	v_mfma_f32_16x16x32_bf16 v[120:123], v[140:143], v[202:205], v[120:123]
	v_mfma_f32_16x16x32_bf16 v[108:111], v[132:135], v[214:217], v[108:111]
	v_mfma_f32_16x16x32_bf16 v[104:107], v[140:143], v[214:217], v[104:107]
	v_mfma_f32_16x16x32_bf16 v[92:95], v[132:135], v[222:225], v[92:95]
	v_mfma_f32_16x16x32_bf16 v[88:91], v[140:143], v[222:225], v[88:91]
	v_mfma_f32_16x16x32_bf16 v[76:79], v[132:135], v[230:233], v[76:79]
	v_mfma_f32_16x16x32_bf16 v[72:75], v[140:143], v[230:233], v[72:75]
	v_mfma_f32_16x16x32_bf16 v[116:119], v[144:147], v[196:199], v[116:119]
	v_mfma_f32_16x16x32_bf16 v[112:115], v[180:183], v[196:199], v[112:115]
	v_mfma_f32_16x16x32_bf16 v[100:103], v[144:147], v[210:213], v[100:103]
	v_mfma_f32_16x16x32_bf16 v[96:99], v[180:183], v[210:213], v[96:99]
	v_mfma_f32_16x16x32_bf16 v[84:87], v[144:147], v[218:221], v[84:87]
	v_mfma_f32_16x16x32_bf16 v[80:83], v[180:183], v[218:221], v[80:83]
	v_mfma_f32_16x16x32_bf16 v[68:71], v[144:147], v[226:229], v[68:71]
	v_mfma_f32_16x16x32_bf16 v[64:67], v[180:183], v[226:229], v[64:67]
	v_mfma_f32_16x16x32_bf16 v[116:119], v[148:151], v[202:205], v[116:119]
	v_mfma_f32_16x16x32_bf16 v[112:115], v[188:191], v[202:205], v[112:115]
	v_mfma_f32_16x16x32_bf16 v[100:103], v[148:151], v[214:217], v[100:103]
	v_mfma_f32_16x16x32_bf16 v[96:99], v[188:191], v[214:217], v[96:99]
	v_mfma_f32_16x16x32_bf16 v[84:87], v[148:151], v[222:225], v[84:87]
	v_mfma_f32_16x16x32_bf16 v[80:83], v[188:191], v[222:225], v[80:83]
	v_mfma_f32_16x16x32_bf16 v[68:71], v[148:151], v[230:233], v[68:71]
	v_mfma_f32_16x16x32_bf16 v[64:67], v[188:191], v[230:233], v[64:67]
	s_setprio 0
	s_barrier
	s_add_u32 s98, s48, s20
	s_addc_u32 s99, s49, s21
	s_add_u32 s100, s50, s20
	s_addc_u32 s101, s51, s21
	s_add_i32 s67, s61, s52
	s_mov_b32 m0, s67
	ds_read_b128 v[196:199], v195 offset:16384
	ds_read_b128 v[202:205], v195 offset:17408
	ds_read_b128 v[210:213], v195 offset:18432
	ds_read_b128 v[214:217], v195 offset:19456
	ds_read_b128 v[218:221], v195 offset:20480
	ds_read_b128 v[222:225], v195 offset:21504
	ds_read_b128 v[226:229], v195 offset:22528
	ds_read_b128 v[230:233], v195 offset:23552
	global_load_lds_dwordx4 v154, s[48:49]
	s_add_i32 m0, s67, 0x2000
	s_add_u32 s68, s48, 0x40000
	s_addc_u32 s69, s49, 0
	s_add_i32 s67, s62, s52
	global_load_lds_dwordx4 v158, s[48:49]
	s_mov_b32 m0, s67
	s_nop 0
	global_load_lds_dwordx4 v154, s[68:69]
	s_add_i32 m0, s67, 0x2000
	s_nop 0
	global_load_lds_dwordx4 v158, s[68:69]
	s_mov_b32 m0, s45
	s_nop 0
	global_load_lds_dwordx4 v152, s[50:51]
	s_mov_b32 m0, s53
	s_nop 0
	global_load_lds_dwordx4 v156, s[50:51]
	s_waitcnt vmcnt(8)
	s_waitcnt lgkmcnt(0)
	s_barrier
	s_setprio 1
	s_waitcnt lgkmcnt(0)
	v_mfma_f32_16x16x32_bf16 v[60:63], v[128:131], v[196:199], v[60:63]
	v_mfma_f32_16x16x32_bf16 v[56:59], v[136:139], v[196:199], v[56:59]
	v_mfma_f32_16x16x32_bf16 v[44:47], v[128:131], v[210:213], v[44:47]
	v_mfma_f32_16x16x32_bf16 v[40:43], v[136:139], v[210:213], v[40:43]
	v_mfma_f32_16x16x32_bf16 v[28:31], v[128:131], v[218:221], v[28:31]
	v_mfma_f32_16x16x32_bf16 v[24:27], v[136:139], v[218:221], v[24:27]
	v_mfma_f32_16x16x32_bf16 v[12:15], v[128:131], v[226:229], v[12:15]
	v_mfma_f32_16x16x32_bf16 v[8:11], v[136:139], v[226:229], v[8:11]
	v_mfma_f32_16x16x32_bf16 v[60:63], v[132:135], v[202:205], v[60:63]
	v_mfma_f32_16x16x32_bf16 v[56:59], v[140:143], v[202:205], v[56:59]
	v_mfma_f32_16x16x32_bf16 v[44:47], v[132:135], v[214:217], v[44:47]
	v_mfma_f32_16x16x32_bf16 v[40:43], v[140:143], v[214:217], v[40:43]
	v_mfma_f32_16x16x32_bf16 v[28:31], v[132:135], v[222:225], v[28:31]
	v_mfma_f32_16x16x32_bf16 v[24:27], v[140:143], v[222:225], v[24:27]
	v_mfma_f32_16x16x32_bf16 v[12:15], v[132:135], v[230:233], v[12:15]
	v_mfma_f32_16x16x32_bf16 v[8:11], v[140:143], v[230:233], v[8:11]
	v_mfma_f32_16x16x32_bf16 v[52:55], v[144:147], v[196:199], v[52:55]
	v_mfma_f32_16x16x32_bf16 v[48:51], v[180:183], v[196:199], v[48:51]
	v_mfma_f32_16x16x32_bf16 v[36:39], v[144:147], v[210:213], v[36:39]
	v_mfma_f32_16x16x32_bf16 v[32:35], v[180:183], v[210:213], v[32:35]
	v_mfma_f32_16x16x32_bf16 v[20:23], v[144:147], v[218:221], v[20:23]
	v_mfma_f32_16x16x32_bf16 v[16:19], v[180:183], v[218:221], v[16:19]
	v_mfma_f32_16x16x32_bf16 v[4:7], v[144:147], v[226:229], v[4:7]
	v_mfma_f32_16x16x32_bf16 v[0:3], v[180:183], v[226:229], v[0:3]
	v_mfma_f32_16x16x32_bf16 v[52:55], v[148:151], v[202:205], v[52:55]
	v_mfma_f32_16x16x32_bf16 v[48:51], v[188:191], v[202:205], v[48:51]
	v_mfma_f32_16x16x32_bf16 v[36:39], v[148:151], v[214:217], v[36:39]
	v_mfma_f32_16x16x32_bf16 v[32:35], v[188:191], v[214:217], v[32:35]
	v_mfma_f32_16x16x32_bf16 v[20:23], v[148:151], v[222:225], v[20:23]
	v_mfma_f32_16x16x32_bf16 v[16:19], v[188:191], v[222:225], v[16:19]
	v_mfma_f32_16x16x32_bf16 v[4:7], v[148:151], v[230:233], v[4:7]
	v_mfma_f32_16x16x32_bf16 v[0:3], v[188:191], v[230:233], v[0:3]
	s_setprio 0
	s_barrier
	s_add_i32 s67, 0, 0x18000
	s_add_i32 s68, 0, 0x1c000
	ds_read_b128 v[128:131], v248
	ds_read_b128 v[132:135], v248 offset:1024
	ds_read_b128 v[136:139], v248 offset:2048
	ds_read_b128 v[140:143], v248 offset:3072
	ds_read_b128 v[144:147], v249
	ds_read_b128 v[148:151], v249 offset:1024
	ds_read_b128 v[180:183], v249 offset:2048
	ds_read_b128 v[188:191], v249 offset:3072
	s_add_u32 s50, s50, 0x40000
	s_addc_u32 s51, s51, 0
	s_mov_b32 m0, s54
	ds_read_b128 v[196:199], v195 offset:32768
	ds_read_b128 v[202:205], v195 offset:33792
	ds_read_b128 v[210:213], v195 offset:34816
	ds_read_b128 v[214:217], v195 offset:35840
	ds_read_b128 v[218:221], v195 offset:36864
	ds_read_b128 v[222:225], v195 offset:37888
	ds_read_b128 v[226:229], v195 offset:38912
	ds_read_b128 v[230:233], v195 offset:39936
	global_load_lds_dwordx4 v152, s[50:51]
	s_mov_b32 m0, s55
	s_nop 0
	global_load_lds_dwordx4 v156, s[50:51]
	s_waitcnt vmcnt(8)
	s_waitcnt lgkmcnt(0)
	s_barrier
	s_setprio 1
	s_waitcnt lgkmcnt(0)
	v_mfma_f32_16x16x32_bf16 v[124:127], v[128:131], v[196:199], v[124:127]
	v_mfma_f32_16x16x32_bf16 v[120:123], v[136:139], v[196:199], v[120:123]
	v_mfma_f32_16x16x32_bf16 v[108:111], v[128:131], v[210:213], v[108:111]
	v_mfma_f32_16x16x32_bf16 v[104:107], v[136:139], v[210:213], v[104:107]
	v_mfma_f32_16x16x32_bf16 v[92:95], v[128:131], v[218:221], v[92:95]
	v_mfma_f32_16x16x32_bf16 v[88:91], v[136:139], v[218:221], v[88:91]
	v_mfma_f32_16x16x32_bf16 v[76:79], v[128:131], v[226:229], v[76:79]
	v_mfma_f32_16x16x32_bf16 v[72:75], v[136:139], v[226:229], v[72:75]
	v_mfma_f32_16x16x32_bf16 v[124:127], v[132:135], v[202:205], v[124:127]
	v_mfma_f32_16x16x32_bf16 v[120:123], v[140:143], v[202:205], v[120:123]
	v_mfma_f32_16x16x32_bf16 v[108:111], v[132:135], v[214:217], v[108:111]
	v_mfma_f32_16x16x32_bf16 v[104:107], v[140:143], v[214:217], v[104:107]
	v_mfma_f32_16x16x32_bf16 v[92:95], v[132:135], v[222:225], v[92:95]
	v_mfma_f32_16x16x32_bf16 v[88:91], v[140:143], v[222:225], v[88:91]
	v_mfma_f32_16x16x32_bf16 v[76:79], v[132:135], v[230:233], v[76:79]
	v_mfma_f32_16x16x32_bf16 v[72:75], v[140:143], v[230:233], v[72:75]
	v_mfma_f32_16x16x32_bf16 v[116:119], v[144:147], v[196:199], v[116:119]
	v_mfma_f32_16x16x32_bf16 v[112:115], v[180:183], v[196:199], v[112:115]
	v_mfma_f32_16x16x32_bf16 v[100:103], v[144:147], v[210:213], v[100:103]
	v_mfma_f32_16x16x32_bf16 v[96:99], v[180:183], v[210:213], v[96:99]
	v_mfma_f32_16x16x32_bf16 v[84:87], v[144:147], v[218:221], v[84:87]
	v_mfma_f32_16x16x32_bf16 v[80:83], v[180:183], v[218:221], v[80:83]
	v_mfma_f32_16x16x32_bf16 v[68:71], v[144:147], v[226:229], v[68:71]
	v_mfma_f32_16x16x32_bf16 v[64:67], v[180:183], v[226:229], v[64:67]
	v_mfma_f32_16x16x32_bf16 v[116:119], v[148:151], v[202:205], v[116:119]
	v_mfma_f32_16x16x32_bf16 v[112:115], v[188:191], v[202:205], v[112:115]
	v_mfma_f32_16x16x32_bf16 v[100:103], v[148:151], v[214:217], v[100:103]
	v_mfma_f32_16x16x32_bf16 v[96:99], v[188:191], v[214:217], v[96:99]
	v_mfma_f32_16x16x32_bf16 v[84:87], v[148:151], v[222:225], v[84:87]
	v_mfma_f32_16x16x32_bf16 v[80:83], v[188:191], v[222:225], v[80:83]
	v_mfma_f32_16x16x32_bf16 v[68:71], v[148:151], v[230:233], v[68:71]
	v_mfma_f32_16x16x32_bf16 v[64:67], v[188:191], v[230:233], v[64:67]
	s_setprio 0
	s_barrier
	s_add_i32 s50, s67, s52
	s_mov_b32 m0, s50
	ds_read_b128 v[196:199], v195 offset:49152
	ds_read_b128 v[202:205], v195 offset:50176
	ds_read_b128 v[210:213], v195 offset:51200
	ds_read_b128 v[214:217], v195 offset:52224
	ds_read_b128 v[218:221], v195 offset:53248
	ds_read_b128 v[222:225], v195 offset:54272
	ds_read_b128 v[226:229], v195 offset:55296
	ds_read_b128 v[230:233], v195 offset:56320
	global_load_lds_dwordx4 v154, s[98:99]
	s_add_i32 m0, s50, 0x2000
	s_add_u32 s48, s48, 0x40080
	s_addc_u32 s49, s49, 0
	s_add_i32 s50, s68, s52
	global_load_lds_dwordx4 v158, s[98:99]
	s_mov_b32 m0, s50
	s_nop 0
	global_load_lds_dwordx4 v154, s[48:49]
	s_add_i32 m0, s50, 0x2000
	s_nop 0
	global_load_lds_dwordx4 v158, s[48:49]
	s_mov_b32 m0, s57
	s_nop 0
	global_load_lds_dwordx4 v152, s[100:101]
	s_mov_b32 m0, s58
	s_nop 0
	global_load_lds_dwordx4 v156, s[100:101]
	s_waitcnt vmcnt(8)
	s_waitcnt lgkmcnt(0)
	s_barrier
	s_setprio 1
	s_waitcnt lgkmcnt(0)
	v_mfma_f32_16x16x32_bf16 v[60:63], v[128:131], v[196:199], v[60:63]
	v_mfma_f32_16x16x32_bf16 v[56:59], v[136:139], v[196:199], v[56:59]
	v_mfma_f32_16x16x32_bf16 v[44:47], v[128:131], v[210:213], v[44:47]
	v_mfma_f32_16x16x32_bf16 v[40:43], v[136:139], v[210:213], v[40:43]
	v_mfma_f32_16x16x32_bf16 v[28:31], v[128:131], v[218:221], v[28:31]
	v_mfma_f32_16x16x32_bf16 v[24:27], v[136:139], v[218:221], v[24:27]
	v_mfma_f32_16x16x32_bf16 v[12:15], v[128:131], v[226:229], v[12:15]
	v_mfma_f32_16x16x32_bf16 v[8:11], v[136:139], v[226:229], v[8:11]
	v_mfma_f32_16x16x32_bf16 v[60:63], v[132:135], v[202:205], v[60:63]
	v_mfma_f32_16x16x32_bf16 v[56:59], v[140:143], v[202:205], v[56:59]
	v_mfma_f32_16x16x32_bf16 v[44:47], v[132:135], v[214:217], v[44:47]
	v_mfma_f32_16x16x32_bf16 v[40:43], v[140:143], v[214:217], v[40:43]
	v_mfma_f32_16x16x32_bf16 v[28:31], v[132:135], v[222:225], v[28:31]
	v_mfma_f32_16x16x32_bf16 v[24:27], v[140:143], v[222:225], v[24:27]
	v_mfma_f32_16x16x32_bf16 v[12:15], v[132:135], v[230:233], v[12:15]
	v_mfma_f32_16x16x32_bf16 v[8:11], v[140:143], v[230:233], v[8:11]
	v_mfma_f32_16x16x32_bf16 v[52:55], v[144:147], v[196:199], v[52:55]
	v_mfma_f32_16x16x32_bf16 v[48:51], v[180:183], v[196:199], v[48:51]
	v_mfma_f32_16x16x32_bf16 v[36:39], v[144:147], v[210:213], v[36:39]
	v_mfma_f32_16x16x32_bf16 v[32:35], v[180:183], v[210:213], v[32:35]
	v_mfma_f32_16x16x32_bf16 v[20:23], v[144:147], v[218:221], v[20:23]
	v_mfma_f32_16x16x32_bf16 v[16:19], v[180:183], v[218:221], v[16:19]
	v_mfma_f32_16x16x32_bf16 v[4:7], v[144:147], v[226:229], v[4:7]
	v_mfma_f32_16x16x32_bf16 v[0:3], v[180:183], v[226:229], v[0:3]
	v_mfma_f32_16x16x32_bf16 v[52:55], v[148:151], v[202:205], v[52:55]
	v_mfma_f32_16x16x32_bf16 v[48:51], v[188:191], v[202:205], v[48:51]
	v_mfma_f32_16x16x32_bf16 v[36:39], v[148:151], v[214:217], v[36:39]
	v_mfma_f32_16x16x32_bf16 v[32:35], v[188:191], v[214:217], v[32:35]
	v_mfma_f32_16x16x32_bf16 v[20:23], v[148:151], v[222:225], v[20:23]
	v_mfma_f32_16x16x32_bf16 v[16:19], v[188:191], v[222:225], v[16:19]
	v_mfma_f32_16x16x32_bf16 v[4:7], v[148:151], v[230:233], v[4:7]
	v_mfma_f32_16x16x32_bf16 v[0:3], v[188:191], v[230:233], v[0:3]
	s_setprio 0
	s_barrier
	s_add_i32 s66, s66, 2
	s_add_u32 s46, s46, 0x100
	s_addc_u32 s47, s47, 0
	s_add_u32 s64, s64, 0x100
	s_addc_u32 s65, s65, 0
	s_cmp_gt_u32 s66, 13
	s_cbranch_scc0 .LBB0_492
	s_and_b64 vcc, exec, s[22:23]
	s_cbranch_vccz .LBB0_495
	s_barrier

.LBB0_577:
	s_ashr_i32 s47, s46, 31
	s_lshl_b64 s[48:49], s[46:47], 19
	s_add_u32 s48, s2, s48
	s_addc_u32 s49, s31, s49
	s_and_b64 s[50:51], s[10:11], exec
	s_cselect_b32 s47, s49, s57
	s_cselect_b32 s53, s48, s56
	s_ashr_i32 s45, s44, 31
	s_lshl_b64 s[50:51], s[44:45], 19
	s_add_u32 s50, s34, s50
	s_addc_u32 s51, s35, s51
	s_and_b64 s[60:61], s[10:11], exec
	s_cselect_b32 s45, s51, s59
	s_cselect_b32 s76, s50, s58
	s_add_u32 s77, s58, 0x100
	v_mov_b32_e32 v0, 0
	s_addc_u32 s78, s59, 0
	s_mov_b32 s79, -2
	v_mov_b32_e32 v1, v0
	v_mov_b32_e32 v2, v0
	v_mov_b32_e32 v3, v0
	v_mov_b32_e32 v32, v0
	v_mov_b32_e32 v33, v0
	v_mov_b32_e32 v34, v0
	v_mov_b32_e32 v35, v0
	v_mov_b32_e32 v4, v0
	v_mov_b32_e32 v5, v0
	v_mov_b32_e32 v6, v0
	v_mov_b32_e32 v7, v0
	v_mov_b32_e32 v36, v0
	v_mov_b32_e32 v37, v0
	v_mov_b32_e32 v38, v0
	v_mov_b32_e32 v39, v0
	v_mov_b32_e32 v8, v0
	v_mov_b32_e32 v9, v0
	v_mov_b32_e32 v10, v0
	v_mov_b32_e32 v11, v0
	v_mov_b32_e32 v40, v0
	v_mov_b32_e32 v41, v0
	v_mov_b32_e32 v42, v0
	v_mov_b32_e32 v43, v0
	v_mov_b32_e32 v16, v0
	v_mov_b32_e32 v17, v0
	v_mov_b32_e32 v18, v0
	v_mov_b32_e32 v19, v0
	v_mov_b32_e32 v48, v0
	v_mov_b32_e32 v49, v0
	v_mov_b32_e32 v50, v0
	v_mov_b32_e32 v51, v0
	v_mov_b32_e32 v20, v0
	v_mov_b32_e32 v21, v0
	v_mov_b32_e32 v22, v0
	v_mov_b32_e32 v23, v0
	v_mov_b32_e32 v52, v0
	v_mov_b32_e32 v53, v0
	v_mov_b32_e32 v54, v0
	v_mov_b32_e32 v55, v0
	v_mov_b32_e32 v12, v0
	v_mov_b32_e32 v13, v0
	v_mov_b32_e32 v14, v0
	v_mov_b32_e32 v15, v0
	v_mov_b32_e32 v44, v0
	v_mov_b32_e32 v45, v0
	v_mov_b32_e32 v46, v0
	v_mov_b32_e32 v47, v0
	v_mov_b32_e32 v24, v0
	v_mov_b32_e32 v25, v0
	v_mov_b32_e32 v26, v0
	v_mov_b32_e32 v27, v0
	v_mov_b32_e32 v56, v0
	v_mov_b32_e32 v57, v0
	v_mov_b32_e32 v58, v0
	v_mov_b32_e32 v59, v0
	v_mov_b32_e32 v28, v0
	v_mov_b32_e32 v29, v0
	v_mov_b32_e32 v30, v0
	v_mov_b32_e32 v31, v0
	v_mov_b32_e32 v60, v0
	v_mov_b32_e32 v61, v0
	v_mov_b32_e32 v62, v0
	v_mov_b32_e32 v63, v0
	v_mov_b32_e32 v64, v0
	v_mov_b32_e32 v65, v0
	v_mov_b32_e32 v66, v0
	v_mov_b32_e32 v67, v0
	v_mov_b32_e32 v112, v0
	v_mov_b32_e32 v113, v0
	v_mov_b32_e32 v114, v0
	v_mov_b32_e32 v115, v0
	v_mov_b32_e32 v68, v0
	v_mov_b32_e32 v69, v0
	v_mov_b32_e32 v70, v0
	v_mov_b32_e32 v71, v0
	v_mov_b32_e32 v132, v0
	v_mov_b32_e32 v133, v0
	v_mov_b32_e32 v134, v0
	v_mov_b32_e32 v135, v0
	v_mov_b32_e32 v88, v0
	v_mov_b32_e32 v89, v0
	v_mov_b32_e32 v90, v0
	v_mov_b32_e32 v91, v0
	v_mov_b32_e32 v136, v0
	v_mov_b32_e32 v137, v0
	v_mov_b32_e32 v138, v0
	v_mov_b32_e32 v139, v0
	v_mov_b32_e32 v96, v0
	v_mov_b32_e32 v97, v0
	v_mov_b32_e32 v98, v0
	v_mov_b32_e32 v99, v0
	v_mov_b32_e32 v148, v0
	v_mov_b32_e32 v149, v0
	v_mov_b32_e32 v150, v0
	v_mov_b32_e32 v151, v0
	v_mov_b32_e32 v100, v0
	v_mov_b32_e32 v101, v0
	v_mov_b32_e32 v102, v0
	v_mov_b32_e32 v103, v0
	v_mov_b32_e32 v152, v0
	v_mov_b32_e32 v153, v0
	v_mov_b32_e32 v154, v0
	v_mov_b32_e32 v155, v0
	v_mov_b32_e32 v92, v0
	v_mov_b32_e32 v93, v0
	v_mov_b32_e32 v94, v0
	v_mov_b32_e32 v95, v0
	v_mov_b32_e32 v144, v0
	v_mov_b32_e32 v145, v0
	v_mov_b32_e32 v146, v0
	v_mov_b32_e32 v147, v0
	v_mov_b32_e32 v104, v0
	v_mov_b32_e32 v105, v0
	v_mov_b32_e32 v106, v0
	v_mov_b32_e32 v107, v0
	v_mov_b32_e32 v156, v0
	v_mov_b32_e32 v157, v0
	v_mov_b32_e32 v158, v0
	v_mov_b32_e32 v159, v0
	v_mov_b32_e32 v108, v0
	v_mov_b32_e32 v109, v0
	v_mov_b32_e32 v110, v0
	v_mov_b32_e32 v111, v0
	v_mov_b32_e32 v160, v0
	v_mov_b32_e32 v161, v0
	v_mov_b32_e32 v162, v0
	v_mov_b32_e32 v163, v0
	v_add_u32_e32 v248, 0x18000, v204
	v_add_u32_e32 v249, 0x1c000, v204
.LBB0_578:
	ds_read_b128 v[72:75], v206
	ds_read_b128 v[76:79], v206 offset:1024
	ds_read_b128 v[80:83], v206 offset:2048
	ds_read_b128 v[84:87], v206 offset:3072
	ds_read_b128 v[116:119], v207
	ds_read_b128 v[120:123], v207 offset:1024
	ds_read_b128 v[124:127], v207 offset:2048
	ds_read_b128 v[128:131], v207 offset:3072
	s_add_u32 s58, s56, 0x100
	s_addc_u32 s59, s57, 0
	s_cmp_eq_u32 s79, 12
	s_cselect_b32 s63, s47, s59
	s_cselect_b32 s62, s53, s58
	s_cselect_b32 s61, s45, s78
	s_cselect_b32 s60, s76, s77
	s_add_i32 m0, s43, 0xc000
	ds_read_b128 v[140:143], v209
	ds_read_b128 v[164:167], v209 offset:1024
	ds_read_b128 v[168:171], v209 offset:2048
	ds_read_b128 v[192:195], v209 offset:3072
	ds_read_b128 v[196:199], v209 offset:4096
	ds_read_b128 v[200:203], v209 offset:5120
	ds_read_b128 v[212:215], v209 offset:6144
	ds_read_b128 v[216:219], v209 offset:7168
	global_load_lds_dwordx4 v184, s[56:57]
	s_add_i32 m0, s43, 0xe000
	s_nop 0
	global_load_lds_dwordx4 v186, s[56:57]
	s_waitcnt vmcnt(8)
	s_waitcnt lgkmcnt(0)
	s_barrier
	s_setprio 1
	s_waitcnt lgkmcnt(0)
	v_mfma_f32_16x16x32_bf16 v[160:163], v[72:75], v[140:143], v[160:163]
	v_mfma_f32_16x16x32_bf16 v[108:111], v[80:83], v[140:143], v[108:111]
	v_mfma_f32_16x16x32_bf16 v[156:159], v[72:75], v[168:171], v[156:159]
	v_mfma_f32_16x16x32_bf16 v[104:107], v[80:83], v[168:171], v[104:107]
	v_mfma_f32_16x16x32_bf16 v[144:147], v[72:75], v[196:199], v[144:147]
	v_mfma_f32_16x16x32_bf16 v[92:95], v[80:83], v[196:199], v[92:95]
	v_mfma_f32_16x16x32_bf16 v[152:155], v[72:75], v[212:215], v[152:155]
	v_mfma_f32_16x16x32_bf16 v[100:103], v[80:83], v[212:215], v[100:103]
	v_mfma_f32_16x16x32_bf16 v[160:163], v[76:79], v[164:167], v[160:163]
	v_mfma_f32_16x16x32_bf16 v[108:111], v[84:87], v[164:167], v[108:111]
	v_mfma_f32_16x16x32_bf16 v[156:159], v[76:79], v[192:195], v[156:159]
	v_mfma_f32_16x16x32_bf16 v[104:107], v[84:87], v[192:195], v[104:107]
	v_mfma_f32_16x16x32_bf16 v[144:147], v[76:79], v[200:203], v[144:147]
	v_mfma_f32_16x16x32_bf16 v[92:95], v[84:87], v[200:203], v[92:95]
	v_mfma_f32_16x16x32_bf16 v[152:155], v[76:79], v[216:219], v[152:155]
	v_mfma_f32_16x16x32_bf16 v[100:103], v[84:87], v[216:219], v[100:103]
	v_mfma_f32_16x16x32_bf16 v[148:151], v[116:119], v[140:143], v[148:151]
	v_mfma_f32_16x16x32_bf16 v[96:99], v[124:127], v[140:143], v[96:99]
	v_mfma_f32_16x16x32_bf16 v[136:139], v[116:119], v[168:171], v[136:139]
	v_mfma_f32_16x16x32_bf16 v[88:91], v[124:127], v[168:171], v[88:91]
	v_mfma_f32_16x16x32_bf16 v[132:135], v[116:119], v[196:199], v[132:135]
	v_mfma_f32_16x16x32_bf16 v[68:71], v[124:127], v[196:199], v[68:71]
	v_mfma_f32_16x16x32_bf16 v[112:115], v[116:119], v[212:215], v[112:115]
	v_mfma_f32_16x16x32_bf16 v[64:67], v[124:127], v[212:215], v[64:67]
	v_mfma_f32_16x16x32_bf16 v[148:151], v[120:123], v[164:167], v[148:151]
	v_mfma_f32_16x16x32_bf16 v[96:99], v[128:131], v[164:167], v[96:99]
	v_mfma_f32_16x16x32_bf16 v[136:139], v[120:123], v[192:195], v[136:139]
	v_mfma_f32_16x16x32_bf16 v[88:91], v[128:131], v[192:195], v[88:91]
	v_mfma_f32_16x16x32_bf16 v[132:135], v[120:123], v[200:203], v[132:135]
	v_mfma_f32_16x16x32_bf16 v[68:71], v[128:131], v[200:203], v[68:71]
	v_mfma_f32_16x16x32_bf16 v[112:115], v[120:123], v[216:219], v[112:115]
	v_mfma_f32_16x16x32_bf16 v[64:67], v[128:131], v[216:219], v[64:67]
	s_setprio 0
	s_barrier
	s_add_u32 s98, s60, s22
	s_addc_u32 s99, s61, s23
	s_add_u32 s100, s62, s22
	s_addc_u32 s101, s63, s23
	s_add_i32 s56, s73, s41
	s_mov_b32 m0, s56
	ds_read_b128 v[140:143], v209 offset:16384
	ds_read_b128 v[164:167], v209 offset:17408
	ds_read_b128 v[168:171], v209 offset:18432
	ds_read_b128 v[192:195], v209 offset:19456
	ds_read_b128 v[196:199], v209 offset:20480
	ds_read_b128 v[200:203], v209 offset:21504
	ds_read_b128 v[212:215], v209 offset:22528
	ds_read_b128 v[216:219], v209 offset:23552
	global_load_lds_dwordx4 v176, s[60:61]
	s_add_i32 m0, s56, 0x2000
	s_add_u32 s56, s60, 0x40000
	s_addc_u32 s57, s61, 0
	s_add_i32 s80, s74, s41
	global_load_lds_dwordx4 v180, s[60:61]
	s_mov_b32 m0, s80
	s_nop 0
	global_load_lds_dwordx4 v176, s[56:57]
	s_add_i32 m0, s80, 0x2000
	s_nop 0
	global_load_lds_dwordx4 v180, s[56:57]
	s_mov_b32 m0, s43
	s_nop 0
	global_load_lds_dwordx4 v174, s[62:63]
	s_mov_b32 m0, s55
	s_nop 0
	global_load_lds_dwordx4 v178, s[62:63]
	s_waitcnt vmcnt(8)
	s_waitcnt lgkmcnt(0)
	s_barrier
	s_setprio 1
	s_waitcnt lgkmcnt(0)
	v_mfma_f32_16x16x32_bf16 v[60:63], v[72:75], v[140:143], v[60:63]
	v_mfma_f32_16x16x32_bf16 v[28:31], v[80:83], v[140:143], v[28:31]
	v_mfma_f32_16x16x32_bf16 v[56:59], v[72:75], v[168:171], v[56:59]
	v_mfma_f32_16x16x32_bf16 v[24:27], v[80:83], v[168:171], v[24:27]
	v_mfma_f32_16x16x32_bf16 v[44:47], v[72:75], v[196:199], v[44:47]
	v_mfma_f32_16x16x32_bf16 v[12:15], v[80:83], v[196:199], v[12:15]
	v_mfma_f32_16x16x32_bf16 v[52:55], v[72:75], v[212:215], v[52:55]
	v_mfma_f32_16x16x32_bf16 v[20:23], v[80:83], v[212:215], v[20:23]
	v_mfma_f32_16x16x32_bf16 v[60:63], v[76:79], v[164:167], v[60:63]
	v_mfma_f32_16x16x32_bf16 v[28:31], v[84:87], v[164:167], v[28:31]
	v_mfma_f32_16x16x32_bf16 v[56:59], v[76:79], v[192:195], v[56:59]
	v_mfma_f32_16x16x32_bf16 v[24:27], v[84:87], v[192:195], v[24:27]
	v_mfma_f32_16x16x32_bf16 v[44:47], v[76:79], v[200:203], v[44:47]
	v_mfma_f32_16x16x32_bf16 v[12:15], v[84:87], v[200:203], v[12:15]
	v_mfma_f32_16x16x32_bf16 v[52:55], v[76:79], v[216:219], v[52:55]
	v_mfma_f32_16x16x32_bf16 v[20:23], v[84:87], v[216:219], v[20:23]
	v_mfma_f32_16x16x32_bf16 v[48:51], v[116:119], v[140:143], v[48:51]
	v_mfma_f32_16x16x32_bf16 v[16:19], v[124:127], v[140:143], v[16:19]
	v_mfma_f32_16x16x32_bf16 v[40:43], v[116:119], v[168:171], v[40:43]
	v_mfma_f32_16x16x32_bf16 v[8:11], v[124:127], v[168:171], v[8:11]
	v_mfma_f32_16x16x32_bf16 v[36:39], v[116:119], v[196:199], v[36:39]
	v_mfma_f32_16x16x32_bf16 v[4:7], v[124:127], v[196:199], v[4:7]
	v_mfma_f32_16x16x32_bf16 v[32:35], v[116:119], v[212:215], v[32:35]
	v_mfma_f32_16x16x32_bf16 v[0:3], v[124:127], v[212:215], v[0:3]
	v_mfma_f32_16x16x32_bf16 v[48:51], v[120:123], v[164:167], v[48:51]
	v_mfma_f32_16x16x32_bf16 v[16:19], v[128:131], v[164:167], v[16:19]
	v_mfma_f32_16x16x32_bf16 v[40:43], v[120:123], v[192:195], v[40:43]
	v_mfma_f32_16x16x32_bf16 v[8:11], v[128:131], v[192:195], v[8:11]
	v_mfma_f32_16x16x32_bf16 v[36:39], v[120:123], v[200:203], v[36:39]
	v_mfma_f32_16x16x32_bf16 v[4:7], v[128:131], v[200:203], v[4:7]
	v_mfma_f32_16x16x32_bf16 v[32:35], v[120:123], v[216:219], v[32:35]
	v_mfma_f32_16x16x32_bf16 v[0:3], v[128:131], v[216:219], v[0:3]
	s_setprio 0
	s_barrier
	s_add_i32 s80, 0, 0x18000
	s_add_i32 s81, 0, 0x1c000
	ds_read_b128 v[72:75], v248
	ds_read_b128 v[76:79], v248 offset:1024
	ds_read_b128 v[80:83], v248 offset:2048
	ds_read_b128 v[84:87], v248 offset:3072
	ds_read_b128 v[116:119], v249
	ds_read_b128 v[120:123], v249 offset:1024
	ds_read_b128 v[124:127], v249 offset:2048
	ds_read_b128 v[128:131], v249 offset:3072
	s_add_u32 s56, s62, 0x40000
	s_addc_u32 s57, s63, 0
	s_mov_b32 m0, s64
	ds_read_b128 v[140:143], v209 offset:32768
	ds_read_b128 v[164:167], v209 offset:33792
	ds_read_b128 v[168:171], v209 offset:34816
	ds_read_b128 v[192:195], v209 offset:35840
	ds_read_b128 v[196:199], v209 offset:36864
	ds_read_b128 v[200:203], v209 offset:37888
	ds_read_b128 v[212:215], v209 offset:38912
	ds_read_b128 v[216:219], v209 offset:39936
	global_load_lds_dwordx4 v174, s[56:57]
	s_mov_b32 m0, s65
	s_nop 0
	global_load_lds_dwordx4 v178, s[56:57]
	s_waitcnt vmcnt(8)
	s_waitcnt lgkmcnt(0)
	s_barrier
	s_setprio 1
	s_waitcnt lgkmcnt(0)
	v_mfma_f32_16x16x32_bf16 v[160:163], v[72:75], v[140:143], v[160:163]
	v_mfma_f32_16x16x32_bf16 v[108:111], v[80:83], v[140:143], v[108:111]
	v_mfma_f32_16x16x32_bf16 v[156:159], v[72:75], v[168:171], v[156:159]
	v_mfma_f32_16x16x32_bf16 v[104:107], v[80:83], v[168:171], v[104:107]
	v_mfma_f32_16x16x32_bf16 v[144:147], v[72:75], v[196:199], v[144:147]
	v_mfma_f32_16x16x32_bf16 v[92:95], v[80:83], v[196:199], v[92:95]
	v_mfma_f32_16x16x32_bf16 v[152:155], v[72:75], v[212:215], v[152:155]
	v_mfma_f32_16x16x32_bf16 v[100:103], v[80:83], v[212:215], v[100:103]
	v_mfma_f32_16x16x32_bf16 v[160:163], v[76:79], v[164:167], v[160:163]
	v_mfma_f32_16x16x32_bf16 v[108:111], v[84:87], v[164:167], v[108:111]
	v_mfma_f32_16x16x32_bf16 v[156:159], v[76:79], v[192:195], v[156:159]
	v_mfma_f32_16x16x32_bf16 v[104:107], v[84:87], v[192:195], v[104:107]
	v_mfma_f32_16x16x32_bf16 v[144:147], v[76:79], v[200:203], v[144:147]
	v_mfma_f32_16x16x32_bf16 v[92:95], v[84:87], v[200:203], v[92:95]
	v_mfma_f32_16x16x32_bf16 v[152:155], v[76:79], v[216:219], v[152:155]
	v_mfma_f32_16x16x32_bf16 v[100:103], v[84:87], v[216:219], v[100:103]
	v_mfma_f32_16x16x32_bf16 v[148:151], v[116:119], v[140:143], v[148:151]
	v_mfma_f32_16x16x32_bf16 v[96:99], v[124:127], v[140:143], v[96:99]
	v_mfma_f32_16x16x32_bf16 v[136:139], v[116:119], v[168:171], v[136:139]
	v_mfma_f32_16x16x32_bf16 v[88:91], v[124:127], v[168:171], v[88:91]
	v_mfma_f32_16x16x32_bf16 v[132:135], v[116:119], v[196:199], v[132:135]
	v_mfma_f32_16x16x32_bf16 v[68:71], v[124:127], v[196:199], v[68:71]
	v_mfma_f32_16x16x32_bf16 v[112:115], v[116:119], v[212:215], v[112:115]
	v_mfma_f32_16x16x32_bf16 v[64:67], v[124:127], v[212:215], v[64:67]
	v_mfma_f32_16x16x32_bf16 v[148:151], v[120:123], v[164:167], v[148:151]
	v_mfma_f32_16x16x32_bf16 v[96:99], v[128:131], v[164:167], v[96:99]
	v_mfma_f32_16x16x32_bf16 v[136:139], v[120:123], v[192:195], v[136:139]
	v_mfma_f32_16x16x32_bf16 v[88:91], v[128:131], v[192:195], v[88:91]
	v_mfma_f32_16x16x32_bf16 v[132:135], v[120:123], v[200:203], v[132:135]
	v_mfma_f32_16x16x32_bf16 v[68:71], v[128:131], v[200:203], v[68:71]
	v_mfma_f32_16x16x32_bf16 v[112:115], v[120:123], v[216:219], v[112:115]
	v_mfma_f32_16x16x32_bf16 v[64:67], v[128:131], v[216:219], v[64:67]
	s_setprio 0
	s_barrier
	s_add_i32 s56, s80, s41
	s_mov_b32 m0, s56
	ds_read_b128 v[140:143], v209 offset:49152
	ds_read_b128 v[164:167], v209 offset:50176
	ds_read_b128 v[168:171], v209 offset:51200
	ds_read_b128 v[192:195], v209 offset:52224
	ds_read_b128 v[196:199], v209 offset:53248
	ds_read_b128 v[200:203], v209 offset:54272
	ds_read_b128 v[212:215], v209 offset:55296
	ds_read_b128 v[216:219], v209 offset:56320
	global_load_lds_dwordx4 v176, s[98:99]
	s_add_i32 m0, s56, 0x2000
	s_add_u32 s56, s60, 0x40080
	s_addc_u32 s57, s61, 0
	s_add_i32 s60, s81, s41
	global_load_lds_dwordx4 v180, s[98:99]
	s_mov_b32 m0, s60
	s_nop 0
	global_load_lds_dwordx4 v176, s[56:57]
	s_add_i32 m0, s60, 0x2000
	s_nop 0
	global_load_lds_dwordx4 v180, s[56:57]
	s_mov_b32 m0, s69
	s_nop 0
	global_load_lds_dwordx4 v174, s[100:101]
	s_mov_b32 m0, s70
	s_nop 0
	global_load_lds_dwordx4 v178, s[100:101]
	s_waitcnt vmcnt(8)
	s_waitcnt lgkmcnt(0)
	s_barrier
	s_setprio 1
	s_waitcnt lgkmcnt(0)
	v_mfma_f32_16x16x32_bf16 v[60:63], v[72:75], v[140:143], v[60:63]
	v_mfma_f32_16x16x32_bf16 v[28:31], v[80:83], v[140:143], v[28:31]
	v_mfma_f32_16x16x32_bf16 v[56:59], v[72:75], v[168:171], v[56:59]
	v_mfma_f32_16x16x32_bf16 v[24:27], v[80:83], v[168:171], v[24:27]
	v_mfma_f32_16x16x32_bf16 v[44:47], v[72:75], v[196:199], v[44:47]
	v_mfma_f32_16x16x32_bf16 v[12:15], v[80:83], v[196:199], v[12:15]
	v_mfma_f32_16x16x32_bf16 v[52:55], v[72:75], v[212:215], v[52:55]
	v_mfma_f32_16x16x32_bf16 v[20:23], v[80:83], v[212:215], v[20:23]
	v_mfma_f32_16x16x32_bf16 v[60:63], v[76:79], v[164:167], v[60:63]
	v_mfma_f32_16x16x32_bf16 v[28:31], v[84:87], v[164:167], v[28:31]
	v_mfma_f32_16x16x32_bf16 v[56:59], v[76:79], v[192:195], v[56:59]
	v_mfma_f32_16x16x32_bf16 v[24:27], v[84:87], v[192:195], v[24:27]
	v_mfma_f32_16x16x32_bf16 v[44:47], v[76:79], v[200:203], v[44:47]
	v_mfma_f32_16x16x32_bf16 v[12:15], v[84:87], v[200:203], v[12:15]
	v_mfma_f32_16x16x32_bf16 v[52:55], v[76:79], v[216:219], v[52:55]
	v_mfma_f32_16x16x32_bf16 v[20:23], v[84:87], v[216:219], v[20:23]
	v_mfma_f32_16x16x32_bf16 v[48:51], v[116:119], v[140:143], v[48:51]
	v_mfma_f32_16x16x32_bf16 v[16:19], v[124:127], v[140:143], v[16:19]
	v_mfma_f32_16x16x32_bf16 v[40:43], v[116:119], v[168:171], v[40:43]
	v_mfma_f32_16x16x32_bf16 v[8:11], v[124:127], v[168:171], v[8:11]
	v_mfma_f32_16x16x32_bf16 v[36:39], v[116:119], v[196:199], v[36:39]
	v_mfma_f32_16x16x32_bf16 v[4:7], v[124:127], v[196:199], v[4:7]
	v_mfma_f32_16x16x32_bf16 v[32:35], v[116:119], v[212:215], v[32:35]
	v_mfma_f32_16x16x32_bf16 v[0:3], v[124:127], v[212:215], v[0:3]
	v_mfma_f32_16x16x32_bf16 v[48:51], v[120:123], v[164:167], v[48:51]
	v_mfma_f32_16x16x32_bf16 v[16:19], v[128:131], v[164:167], v[16:19]
	v_mfma_f32_16x16x32_bf16 v[40:43], v[120:123], v[192:195], v[40:43]
	v_mfma_f32_16x16x32_bf16 v[8:11], v[128:131], v[192:195], v[8:11]
	v_mfma_f32_16x16x32_bf16 v[36:39], v[120:123], v[200:203], v[36:39]
	v_mfma_f32_16x16x32_bf16 v[4:7], v[128:131], v[200:203], v[4:7]
	v_mfma_f32_16x16x32_bf16 v[32:35], v[120:123], v[216:219], v[32:35]
	v_mfma_f32_16x16x32_bf16 v[0:3], v[128:131], v[216:219], v[0:3]
	s_setprio 0
	s_barrier
	s_add_i32 s79, s79, 2
	s_add_u32 s77, s77, 0x100
	s_addc_u32 s78, s78, 0
	s_cmp_gt_u32 s79, 13
	s_mov_b64 s[56:57], s[58:59]
	s_cbranch_scc0 .LBB0_578
	s_and_b64 vcc, exec, s[24:25]
	s_cbranch_vccz .LBB0_581
	s_barrier

.LBB0_740:
	s_add_u32 s60, s38, 0x100
	v_mov_b32_e32 v0, 0
	s_addc_u32 s61, s39, 0
	s_mov_b32 s62, -2
	s_waitcnt lgkmcnt(0)
	v_mov_b32_e32 v1, v0
	v_mov_b32_e32 v2, v0
	v_mov_b32_e32 v3, v0
	v_mov_b32_e32 v4, v0
	v_mov_b32_e32 v5, v0
	v_mov_b32_e32 v6, v0
	v_mov_b32_e32 v7, v0
	v_mov_b32_e32 v16, v0
	v_mov_b32_e32 v17, v0
	v_mov_b32_e32 v18, v0
	v_mov_b32_e32 v19, v0
	v_mov_b32_e32 v20, v0
	v_mov_b32_e32 v21, v0
	v_mov_b32_e32 v22, v0
	v_mov_b32_e32 v23, v0
	v_mov_b32_e32 v32, v0
	v_mov_b32_e32 v33, v0
	v_mov_b32_e32 v34, v0
	v_mov_b32_e32 v35, v0
	v_mov_b32_e32 v36, v0
	v_mov_b32_e32 v37, v0
	v_mov_b32_e32 v38, v0
	v_mov_b32_e32 v39, v0
	v_mov_b32_e32 v48, v0
	v_mov_b32_e32 v49, v0
	v_mov_b32_e32 v50, v0
	v_mov_b32_e32 v51, v0
	v_mov_b32_e32 v52, v0
	v_mov_b32_e32 v53, v0
	v_mov_b32_e32 v54, v0
	v_mov_b32_e32 v55, v0
	v_mov_b32_e32 v8, v0
	v_mov_b32_e32 v9, v0
	v_mov_b32_e32 v10, v0
	v_mov_b32_e32 v11, v0
	v_mov_b32_e32 v12, v0
	v_mov_b32_e32 v13, v0
	v_mov_b32_e32 v14, v0
	v_mov_b32_e32 v15, v0
	v_mov_b32_e32 v24, v0
	v_mov_b32_e32 v25, v0
	v_mov_b32_e32 v26, v0
	v_mov_b32_e32 v27, v0
	v_mov_b32_e32 v28, v0
	v_mov_b32_e32 v29, v0
	v_mov_b32_e32 v30, v0
	v_mov_b32_e32 v31, v0
	v_mov_b32_e32 v40, v0
	v_mov_b32_e32 v41, v0
	v_mov_b32_e32 v42, v0
	v_mov_b32_e32 v43, v0
	v_mov_b32_e32 v44, v0
	v_mov_b32_e32 v45, v0
	v_mov_b32_e32 v46, v0
	v_mov_b32_e32 v47, v0
	v_mov_b32_e32 v56, v0
	v_mov_b32_e32 v57, v0
	v_mov_b32_e32 v58, v0
	v_mov_b32_e32 v59, v0
	v_mov_b32_e32 v60, v0
	v_mov_b32_e32 v61, v0
	v_mov_b32_e32 v62, v0
	v_mov_b32_e32 v63, v0
	v_mov_b32_e32 v64, v0
	v_mov_b32_e32 v65, v0
	v_mov_b32_e32 v66, v0
	v_mov_b32_e32 v67, v0
	v_mov_b32_e32 v68, v0
	v_mov_b32_e32 v69, v0
	v_mov_b32_e32 v70, v0
	v_mov_b32_e32 v71, v0
	v_mov_b32_e32 v80, v0
	v_mov_b32_e32 v81, v0
	v_mov_b32_e32 v82, v0
	v_mov_b32_e32 v83, v0
	v_mov_b32_e32 v84, v0
	v_mov_b32_e32 v85, v0
	v_mov_b32_e32 v86, v0
	v_mov_b32_e32 v87, v0
	v_mov_b32_e32 v96, v0
	v_mov_b32_e32 v97, v0
	v_mov_b32_e32 v98, v0
	v_mov_b32_e32 v99, v0
	v_mov_b32_e32 v100, v0
	v_mov_b32_e32 v101, v0
	v_mov_b32_e32 v102, v0
	v_mov_b32_e32 v103, v0
	v_mov_b32_e32 v112, v0
	v_mov_b32_e32 v113, v0
	v_mov_b32_e32 v114, v0
	v_mov_b32_e32 v115, v0
	v_mov_b32_e32 v116, v0
	v_mov_b32_e32 v117, v0
	v_mov_b32_e32 v118, v0
	v_mov_b32_e32 v119, v0
	v_mov_b32_e32 v72, v0
	v_mov_b32_e32 v73, v0
	v_mov_b32_e32 v74, v0
	v_mov_b32_e32 v75, v0
	v_mov_b32_e32 v76, v0
	v_mov_b32_e32 v77, v0
	v_mov_b32_e32 v78, v0
	v_mov_b32_e32 v79, v0
	v_mov_b32_e32 v88, v0
	v_mov_b32_e32 v89, v0
	v_mov_b32_e32 v90, v0
	v_mov_b32_e32 v91, v0
	v_mov_b32_e32 v92, v0
	v_mov_b32_e32 v93, v0
	v_mov_b32_e32 v94, v0
	v_mov_b32_e32 v95, v0
	v_mov_b32_e32 v104, v0
	v_mov_b32_e32 v105, v0
	v_mov_b32_e32 v106, v0
	v_mov_b32_e32 v107, v0
	v_mov_b32_e32 v108, v0
	v_mov_b32_e32 v109, v0
	v_mov_b32_e32 v110, v0
	v_mov_b32_e32 v111, v0
	v_mov_b32_e32 v120, v0
	v_mov_b32_e32 v121, v0
	v_mov_b32_e32 v122, v0
	v_mov_b32_e32 v123, v0
	v_mov_b32_e32 v124, v0
	v_mov_b32_e32 v125, v0
	v_mov_b32_e32 v126, v0
	v_mov_b32_e32 v127, v0
	v_add_u32_e32 v248, 0x18000, v192
	v_add_u32_e32 v249, 0x1c000, v192
.LBB0_741:
	ds_read_b128 v[128:131], v194
	ds_read_b128 v[132:135], v194 offset:1024
	ds_read_b128 v[136:139], v194 offset:2048
	ds_read_b128 v[140:143], v194 offset:3072
	ds_read_b128 v[144:147], v195
	ds_read_b128 v[148:151], v195 offset:1024
	ds_read_b128 v[168:171], v195 offset:2048
	ds_read_b128 v[174:177], v195 offset:3072
	s_add_u32 s38, s36, 0x100
	s_addc_u32 s39, s37, 0
	s_cmp_eq_u32 s62, 40
	s_cselect_b32 s43, s11, s39
	s_cselect_b32 s42, s10, s38
	s_cselect_b32 s41, s25, s61
	s_cselect_b32 s40, s24, s60
	s_add_i32 m0, s45, 0xc000
	ds_read_b128 v[178:181], v196
	ds_read_b128 v[182:185], v196 offset:1024
	ds_read_b128 v[186:189], v196 offset:2048
	ds_read_b128 v[198:201], v196 offset:3072
	ds_read_b128 v[202:205], v196 offset:4096
	ds_read_b128 v[210:213], v196 offset:5120
	ds_read_b128 v[214:217], v196 offset:6144
	ds_read_b128 v[218:221], v196 offset:7168
	global_load_lds_dwordx4 v160, s[36:37]
	s_add_i32 m0, s45, 0xe000
	s_nop 0
	global_load_lds_dwordx4 v162, s[36:37]
	s_waitcnt vmcnt(8)
	s_waitcnt lgkmcnt(0)
	s_barrier
	s_setprio 1
	s_waitcnt lgkmcnt(0)
	v_mfma_f32_16x16x32_bf16 v[124:127], v[128:131], v[178:181], v[124:127]
	v_mfma_f32_16x16x32_bf16 v[120:123], v[136:139], v[178:181], v[120:123]
	v_mfma_f32_16x16x32_bf16 v[108:111], v[128:131], v[186:189], v[108:111]
	v_mfma_f32_16x16x32_bf16 v[104:107], v[136:139], v[186:189], v[104:107]
	v_mfma_f32_16x16x32_bf16 v[92:95], v[128:131], v[202:205], v[92:95]
	v_mfma_f32_16x16x32_bf16 v[88:91], v[136:139], v[202:205], v[88:91]
	v_mfma_f32_16x16x32_bf16 v[76:79], v[128:131], v[214:217], v[76:79]
	v_mfma_f32_16x16x32_bf16 v[72:75], v[136:139], v[214:217], v[72:75]
	v_mfma_f32_16x16x32_bf16 v[124:127], v[132:135], v[182:185], v[124:127]
	v_mfma_f32_16x16x32_bf16 v[120:123], v[140:143], v[182:185], v[120:123]
	v_mfma_f32_16x16x32_bf16 v[108:111], v[132:135], v[198:201], v[108:111]
	v_mfma_f32_16x16x32_bf16 v[104:107], v[140:143], v[198:201], v[104:107]
	v_mfma_f32_16x16x32_bf16 v[92:95], v[132:135], v[210:213], v[92:95]
	v_mfma_f32_16x16x32_bf16 v[88:91], v[140:143], v[210:213], v[88:91]
	v_mfma_f32_16x16x32_bf16 v[76:79], v[132:135], v[218:221], v[76:79]
	v_mfma_f32_16x16x32_bf16 v[72:75], v[140:143], v[218:221], v[72:75]
	v_mfma_f32_16x16x32_bf16 v[116:119], v[144:147], v[178:181], v[116:119]
	v_mfma_f32_16x16x32_bf16 v[112:115], v[168:171], v[178:181], v[112:115]
	v_mfma_f32_16x16x32_bf16 v[100:103], v[144:147], v[186:189], v[100:103]
	v_mfma_f32_16x16x32_bf16 v[96:99], v[168:171], v[186:189], v[96:99]
	v_mfma_f32_16x16x32_bf16 v[84:87], v[144:147], v[202:205], v[84:87]
	v_mfma_f32_16x16x32_bf16 v[80:83], v[168:171], v[202:205], v[80:83]
	v_mfma_f32_16x16x32_bf16 v[68:71], v[144:147], v[214:217], v[68:71]
	v_mfma_f32_16x16x32_bf16 v[64:67], v[168:171], v[214:217], v[64:67]
	v_mfma_f32_16x16x32_bf16 v[116:119], v[148:151], v[182:185], v[116:119]
	v_mfma_f32_16x16x32_bf16 v[112:115], v[174:177], v[182:185], v[112:115]
	v_mfma_f32_16x16x32_bf16 v[100:103], v[148:151], v[198:201], v[100:103]
	v_mfma_f32_16x16x32_bf16 v[96:99], v[174:177], v[198:201], v[96:99]
	v_mfma_f32_16x16x32_bf16 v[84:87], v[148:151], v[210:213], v[84:87]
	v_mfma_f32_16x16x32_bf16 v[80:83], v[174:177], v[210:213], v[80:83]
	v_mfma_f32_16x16x32_bf16 v[68:71], v[148:151], v[218:221], v[68:71]
	v_mfma_f32_16x16x32_bf16 v[64:67], v[174:177], v[218:221], v[64:67]
	s_setprio 0
	s_barrier
	s_add_u32 s98, s40, s20
	s_addc_u32 s99, s41, s21
	s_add_u32 s100, s42, s20
	s_addc_u32 s101, s43, s21
	s_add_i32 s36, s54, s44
	s_mov_b32 m0, s36
	ds_read_b128 v[178:181], v196 offset:16384
	ds_read_b128 v[182:185], v196 offset:17408
	ds_read_b128 v[186:189], v196 offset:18432
	ds_read_b128 v[198:201], v196 offset:19456
	ds_read_b128 v[202:205], v196 offset:20480
	ds_read_b128 v[210:213], v196 offset:21504
	ds_read_b128 v[214:217], v196 offset:22528
	ds_read_b128 v[218:221], v196 offset:23552
	global_load_lds_dwordx4 v154, s[40:41]
	s_add_i32 m0, s36, 0x2000
	s_add_u32 s36, s40, 0xb0000
	s_addc_u32 s37, s41, 0
	s_add_i32 s63, s55, s44
	global_load_lds_dwordx4 v158, s[40:41]
	s_mov_b32 m0, s63
	s_nop 0
	global_load_lds_dwordx4 v154, s[36:37]
	s_add_i32 m0, s63, 0x2000
	s_nop 0
	global_load_lds_dwordx4 v158, s[36:37]
	s_mov_b32 m0, s45
	s_nop 0
	global_load_lds_dwordx4 v152, s[42:43]
	s_mov_b32 m0, s46
	s_nop 0
	global_load_lds_dwordx4 v156, s[42:43]
	s_waitcnt vmcnt(8)
	s_waitcnt lgkmcnt(0)
	s_barrier
	s_setprio 1
	s_waitcnt lgkmcnt(0)
	v_mfma_f32_16x16x32_bf16 v[60:63], v[128:131], v[178:181], v[60:63]
	v_mfma_f32_16x16x32_bf16 v[56:59], v[136:139], v[178:181], v[56:59]
	v_mfma_f32_16x16x32_bf16 v[44:47], v[128:131], v[186:189], v[44:47]
	v_mfma_f32_16x16x32_bf16 v[40:43], v[136:139], v[186:189], v[40:43]
	v_mfma_f32_16x16x32_bf16 v[28:31], v[128:131], v[202:205], v[28:31]
	v_mfma_f32_16x16x32_bf16 v[24:27], v[136:139], v[202:205], v[24:27]
	v_mfma_f32_16x16x32_bf16 v[12:15], v[128:131], v[214:217], v[12:15]
	v_mfma_f32_16x16x32_bf16 v[8:11], v[136:139], v[214:217], v[8:11]
	v_mfma_f32_16x16x32_bf16 v[60:63], v[132:135], v[182:185], v[60:63]
	v_mfma_f32_16x16x32_bf16 v[56:59], v[140:143], v[182:185], v[56:59]
	v_mfma_f32_16x16x32_bf16 v[44:47], v[132:135], v[198:201], v[44:47]
	v_mfma_f32_16x16x32_bf16 v[40:43], v[140:143], v[198:201], v[40:43]
	v_mfma_f32_16x16x32_bf16 v[28:31], v[132:135], v[210:213], v[28:31]
	v_mfma_f32_16x16x32_bf16 v[24:27], v[140:143], v[210:213], v[24:27]
	v_mfma_f32_16x16x32_bf16 v[12:15], v[132:135], v[218:221], v[12:15]
	v_mfma_f32_16x16x32_bf16 v[8:11], v[140:143], v[218:221], v[8:11]
	v_mfma_f32_16x16x32_bf16 v[52:55], v[144:147], v[178:181], v[52:55]
	v_mfma_f32_16x16x32_bf16 v[48:51], v[168:171], v[178:181], v[48:51]
	v_mfma_f32_16x16x32_bf16 v[36:39], v[144:147], v[186:189], v[36:39]
	v_mfma_f32_16x16x32_bf16 v[32:35], v[168:171], v[186:189], v[32:35]
	v_mfma_f32_16x16x32_bf16 v[20:23], v[144:147], v[202:205], v[20:23]
	v_mfma_f32_16x16x32_bf16 v[16:19], v[168:171], v[202:205], v[16:19]
	v_mfma_f32_16x16x32_bf16 v[4:7], v[144:147], v[214:217], v[4:7]
	v_mfma_f32_16x16x32_bf16 v[0:3], v[168:171], v[214:217], v[0:3]
	v_mfma_f32_16x16x32_bf16 v[52:55], v[148:151], v[182:185], v[52:55]
	v_mfma_f32_16x16x32_bf16 v[48:51], v[174:177], v[182:185], v[48:51]
	v_mfma_f32_16x16x32_bf16 v[36:39], v[148:151], v[198:201], v[36:39]
	v_mfma_f32_16x16x32_bf16 v[32:35], v[174:177], v[198:201], v[32:35]
	v_mfma_f32_16x16x32_bf16 v[20:23], v[148:151], v[210:213], v[20:23]
	v_mfma_f32_16x16x32_bf16 v[16:19], v[174:177], v[210:213], v[16:19]
	v_mfma_f32_16x16x32_bf16 v[4:7], v[148:151], v[218:221], v[4:7]
	v_mfma_f32_16x16x32_bf16 v[0:3], v[174:177], v[218:221], v[0:3]
	s_setprio 0
	s_barrier
	s_add_i32 s63, 0, 0x18000
	s_add_i32 s64, 0, 0x1c000
	ds_read_b128 v[128:131], v248
	ds_read_b128 v[132:135], v248 offset:1024
	ds_read_b128 v[136:139], v248 offset:2048
	ds_read_b128 v[140:143], v248 offset:3072
	ds_read_b128 v[144:147], v249
	ds_read_b128 v[148:151], v249 offset:1024
	ds_read_b128 v[168:171], v249 offset:2048
	ds_read_b128 v[174:177], v249 offset:3072
	s_add_u32 s36, s42, 0xb0000
	s_addc_u32 s37, s43, 0
	s_mov_b32 m0, s47
	ds_read_b128 v[178:181], v196 offset:32768
	ds_read_b128 v[182:185], v196 offset:33792
	ds_read_b128 v[186:189], v196 offset:34816
	ds_read_b128 v[198:201], v196 offset:35840
	ds_read_b128 v[202:205], v196 offset:36864
	ds_read_b128 v[210:213], v196 offset:37888
	ds_read_b128 v[214:217], v196 offset:38912
	ds_read_b128 v[218:221], v196 offset:39936
	global_load_lds_dwordx4 v152, s[36:37]
	s_mov_b32 m0, s48
	s_nop 0
	global_load_lds_dwordx4 v156, s[36:37]
	s_waitcnt vmcnt(8)
	s_waitcnt lgkmcnt(0)
	s_barrier
	s_setprio 1
	s_waitcnt lgkmcnt(0)
	v_mfma_f32_16x16x32_bf16 v[124:127], v[128:131], v[178:181], v[124:127]
	v_mfma_f32_16x16x32_bf16 v[120:123], v[136:139], v[178:181], v[120:123]
	v_mfma_f32_16x16x32_bf16 v[108:111], v[128:131], v[186:189], v[108:111]
	v_mfma_f32_16x16x32_bf16 v[104:107], v[136:139], v[186:189], v[104:107]
	v_mfma_f32_16x16x32_bf16 v[92:95], v[128:131], v[202:205], v[92:95]
	v_mfma_f32_16x16x32_bf16 v[88:91], v[136:139], v[202:205], v[88:91]
	v_mfma_f32_16x16x32_bf16 v[76:79], v[128:131], v[214:217], v[76:79]
	v_mfma_f32_16x16x32_bf16 v[72:75], v[136:139], v[214:217], v[72:75]
	v_mfma_f32_16x16x32_bf16 v[124:127], v[132:135], v[182:185], v[124:127]
	v_mfma_f32_16x16x32_bf16 v[120:123], v[140:143], v[182:185], v[120:123]
	v_mfma_f32_16x16x32_bf16 v[108:111], v[132:135], v[198:201], v[108:111]
	v_mfma_f32_16x16x32_bf16 v[104:107], v[140:143], v[198:201], v[104:107]
	v_mfma_f32_16x16x32_bf16 v[92:95], v[132:135], v[210:213], v[92:95]
	v_mfma_f32_16x16x32_bf16 v[88:91], v[140:143], v[210:213], v[88:91]
	v_mfma_f32_16x16x32_bf16 v[76:79], v[132:135], v[218:221], v[76:79]
	v_mfma_f32_16x16x32_bf16 v[72:75], v[140:143], v[218:221], v[72:75]
	v_mfma_f32_16x16x32_bf16 v[116:119], v[144:147], v[178:181], v[116:119]
	v_mfma_f32_16x16x32_bf16 v[112:115], v[168:171], v[178:181], v[112:115]
	v_mfma_f32_16x16x32_bf16 v[100:103], v[144:147], v[186:189], v[100:103]
	v_mfma_f32_16x16x32_bf16 v[96:99], v[168:171], v[186:189], v[96:99]
	v_mfma_f32_16x16x32_bf16 v[84:87], v[144:147], v[202:205], v[84:87]
	v_mfma_f32_16x16x32_bf16 v[80:83], v[168:171], v[202:205], v[80:83]
	v_mfma_f32_16x16x32_bf16 v[68:71], v[144:147], v[214:217], v[68:71]
	v_mfma_f32_16x16x32_bf16 v[64:67], v[168:171], v[214:217], v[64:67]
	v_mfma_f32_16x16x32_bf16 v[116:119], v[148:151], v[182:185], v[116:119]
	v_mfma_f32_16x16x32_bf16 v[112:115], v[174:177], v[182:185], v[112:115]
	v_mfma_f32_16x16x32_bf16 v[100:103], v[148:151], v[198:201], v[100:103]
	v_mfma_f32_16x16x32_bf16 v[96:99], v[174:177], v[198:201], v[96:99]
	v_mfma_f32_16x16x32_bf16 v[84:87], v[148:151], v[210:213], v[84:87]
	v_mfma_f32_16x16x32_bf16 v[80:83], v[174:177], v[210:213], v[80:83]
	v_mfma_f32_16x16x32_bf16 v[68:71], v[148:151], v[218:221], v[68:71]
	v_mfma_f32_16x16x32_bf16 v[64:67], v[174:177], v[218:221], v[64:67]
	s_setprio 0
	s_barrier
	s_add_i32 s36, s63, s44
	s_mov_b32 m0, s36
	ds_read_b128 v[178:181], v196 offset:49152
	ds_read_b128 v[182:185], v196 offset:50176
	ds_read_b128 v[186:189], v196 offset:51200
	ds_read_b128 v[198:201], v196 offset:52224
	ds_read_b128 v[202:205], v196 offset:53248
	ds_read_b128 v[210:213], v196 offset:54272
	ds_read_b128 v[214:217], v196 offset:55296
	ds_read_b128 v[218:221], v196 offset:56320
	global_load_lds_dwordx4 v154, s[98:99]
	s_add_i32 m0, s36, 0x2000
	s_add_u32 s36, s40, 0xb0080
	s_addc_u32 s37, s41, 0
	s_add_i32 s40, s64, s44
	global_load_lds_dwordx4 v158, s[98:99]
	s_mov_b32 m0, s40
	s_nop 0
	global_load_lds_dwordx4 v154, s[36:37]
	s_add_i32 m0, s40, 0x2000
	s_nop 0
	global_load_lds_dwordx4 v158, s[36:37]
	s_mov_b32 m0, s50
	s_nop 0
	global_load_lds_dwordx4 v152, s[100:101]
	s_mov_b32 m0, s51
	s_nop 0
	global_load_lds_dwordx4 v156, s[100:101]
	s_waitcnt vmcnt(8)
	s_waitcnt lgkmcnt(0)
	s_barrier
	s_setprio 1
	s_waitcnt lgkmcnt(0)
	v_mfma_f32_16x16x32_bf16 v[60:63], v[128:131], v[178:181], v[60:63]
	v_mfma_f32_16x16x32_bf16 v[56:59], v[136:139], v[178:181], v[56:59]
	v_mfma_f32_16x16x32_bf16 v[44:47], v[128:131], v[186:189], v[44:47]
	v_mfma_f32_16x16x32_bf16 v[40:43], v[136:139], v[186:189], v[40:43]
	v_mfma_f32_16x16x32_bf16 v[28:31], v[128:131], v[202:205], v[28:31]
	v_mfma_f32_16x16x32_bf16 v[24:27], v[136:139], v[202:205], v[24:27]
	v_mfma_f32_16x16x32_bf16 v[12:15], v[128:131], v[214:217], v[12:15]
	v_mfma_f32_16x16x32_bf16 v[8:11], v[136:139], v[214:217], v[8:11]
	v_mfma_f32_16x16x32_bf16 v[60:63], v[132:135], v[182:185], v[60:63]
	v_mfma_f32_16x16x32_bf16 v[56:59], v[140:143], v[182:185], v[56:59]
	v_mfma_f32_16x16x32_bf16 v[44:47], v[132:135], v[198:201], v[44:47]
	v_mfma_f32_16x16x32_bf16 v[40:43], v[140:143], v[198:201], v[40:43]
	v_mfma_f32_16x16x32_bf16 v[28:31], v[132:135], v[210:213], v[28:31]
	v_mfma_f32_16x16x32_bf16 v[24:27], v[140:143], v[210:213], v[24:27]
	v_mfma_f32_16x16x32_bf16 v[12:15], v[132:135], v[218:221], v[12:15]
	v_mfma_f32_16x16x32_bf16 v[8:11], v[140:143], v[218:221], v[8:11]
	v_mfma_f32_16x16x32_bf16 v[52:55], v[144:147], v[178:181], v[52:55]
	v_mfma_f32_16x16x32_bf16 v[48:51], v[168:171], v[178:181], v[48:51]
	v_mfma_f32_16x16x32_bf16 v[36:39], v[144:147], v[186:189], v[36:39]
	v_mfma_f32_16x16x32_bf16 v[32:35], v[168:171], v[186:189], v[32:35]
	v_mfma_f32_16x16x32_bf16 v[20:23], v[144:147], v[202:205], v[20:23]
	v_mfma_f32_16x16x32_bf16 v[16:19], v[168:171], v[202:205], v[16:19]
	v_mfma_f32_16x16x32_bf16 v[4:7], v[144:147], v[214:217], v[4:7]
	v_mfma_f32_16x16x32_bf16 v[0:3], v[168:171], v[214:217], v[0:3]
	v_mfma_f32_16x16x32_bf16 v[52:55], v[148:151], v[182:185], v[52:55]
	v_mfma_f32_16x16x32_bf16 v[48:51], v[174:177], v[182:185], v[48:51]
	v_mfma_f32_16x16x32_bf16 v[36:39], v[148:151], v[198:201], v[36:39]
	v_mfma_f32_16x16x32_bf16 v[32:35], v[174:177], v[198:201], v[32:35]
	v_mfma_f32_16x16x32_bf16 v[20:23], v[148:151], v[210:213], v[20:23]
	v_mfma_f32_16x16x32_bf16 v[16:19], v[174:177], v[210:213], v[16:19]
	v_mfma_f32_16x16x32_bf16 v[4:7], v[148:151], v[218:221], v[4:7]
	v_mfma_f32_16x16x32_bf16 v[0:3], v[174:177], v[218:221], v[0:3]
	s_setprio 0
	s_barrier
	s_add_i32 s62, s62, 2
	s_add_u32 s60, s60, 0x100
	s_addc_u32 s61, s61, 0
	s_cmp_gt_u32 s62, 41
	s_mov_b64 s[36:37], s[38:39]
	s_cbranch_scc0 .LBB0_741
	s_and_b64 vcc, exec, s[22:23]
	s_cbranch_vccz .LBB0_744
	s_barrier

.LBB0_835:
	s_ashr_i32 s29, s28, 31
	s_lshl_b64 s[30:31], s[28:29], 19
	s_add_u32 s30, s12, s30
	s_addc_u32 s31, s13, s31
	s_and_b64 s[34:35], s[4:5], exec
	s_cselect_b32 s29, s31, s41
	s_cselect_b32 s37, s30, s40
	s_ashr_i32 s27, s26, 31
	s_lshl_b64 s[34:35], s[26:27], 19
	s_add_u32 s34, s2, s34
	s_addc_u32 s35, s46, s35
	s_and_b64 s[44:45], s[4:5], exec
	s_cselect_b32 s27, s35, s43
	s_cselect_b32 s39, s34, s42
	s_add_u32 s40, s40, 0x40080
	s_addc_u32 s41, s41, 0
	s_add_u32 s61, s42, 0x100
	v_mov_b32_e32 v0, 0
	s_addc_u32 s62, s43, 0
	s_mov_b32 s63, -2
	v_mov_b32_e32 v1, v0
	v_mov_b32_e32 v2, v0
	v_mov_b32_e32 v3, v0
	v_mov_b32_e32 v4, v0
	v_mov_b32_e32 v5, v0
	v_mov_b32_e32 v6, v0
	v_mov_b32_e32 v7, v0
	v_mov_b32_e32 v16, v0
	v_mov_b32_e32 v17, v0
	v_mov_b32_e32 v18, v0
	v_mov_b32_e32 v19, v0
	v_mov_b32_e32 v20, v0
	v_mov_b32_e32 v21, v0
	v_mov_b32_e32 v22, v0
	v_mov_b32_e32 v23, v0
	v_mov_b32_e32 v32, v0
	v_mov_b32_e32 v33, v0
	v_mov_b32_e32 v34, v0
	v_mov_b32_e32 v35, v0
	v_mov_b32_e32 v36, v0
	v_mov_b32_e32 v37, v0
	v_mov_b32_e32 v38, v0
	v_mov_b32_e32 v39, v0
	v_mov_b32_e32 v48, v0
	v_mov_b32_e32 v49, v0
	v_mov_b32_e32 v50, v0
	v_mov_b32_e32 v51, v0
	v_mov_b32_e32 v52, v0
	v_mov_b32_e32 v53, v0
	v_mov_b32_e32 v54, v0
	v_mov_b32_e32 v55, v0
	v_mov_b32_e32 v8, v0
	v_mov_b32_e32 v9, v0
	v_mov_b32_e32 v10, v0
	v_mov_b32_e32 v11, v0
	v_mov_b32_e32 v12, v0
	v_mov_b32_e32 v13, v0
	v_mov_b32_e32 v14, v0
	v_mov_b32_e32 v15, v0
	v_mov_b32_e32 v24, v0
	v_mov_b32_e32 v25, v0
	v_mov_b32_e32 v26, v0
	v_mov_b32_e32 v27, v0
	v_mov_b32_e32 v28, v0
	v_mov_b32_e32 v29, v0
	v_mov_b32_e32 v30, v0
	v_mov_b32_e32 v31, v0
	v_mov_b32_e32 v40, v0
	v_mov_b32_e32 v41, v0
	v_mov_b32_e32 v42, v0
	v_mov_b32_e32 v43, v0
	v_mov_b32_e32 v44, v0
	v_mov_b32_e32 v45, v0
	v_mov_b32_e32 v46, v0
	v_mov_b32_e32 v47, v0
	v_mov_b32_e32 v56, v0
	v_mov_b32_e32 v57, v0
	v_mov_b32_e32 v58, v0
	v_mov_b32_e32 v59, v0
	v_mov_b32_e32 v60, v0
	v_mov_b32_e32 v61, v0
	v_mov_b32_e32 v62, v0
	v_mov_b32_e32 v63, v0
	v_mov_b32_e32 v64, v0
	v_mov_b32_e32 v65, v0
	v_mov_b32_e32 v66, v0
	v_mov_b32_e32 v67, v0
	v_mov_b32_e32 v68, v0
	v_mov_b32_e32 v69, v0
	v_mov_b32_e32 v70, v0
	v_mov_b32_e32 v71, v0
	v_mov_b32_e32 v80, v0
	v_mov_b32_e32 v81, v0
	v_mov_b32_e32 v82, v0
	v_mov_b32_e32 v83, v0
	v_mov_b32_e32 v84, v0
	v_mov_b32_e32 v85, v0
	v_mov_b32_e32 v86, v0
	v_mov_b32_e32 v87, v0
	v_mov_b32_e32 v128, v0
	v_mov_b32_e32 v129, v0
	v_mov_b32_e32 v130, v0
	v_mov_b32_e32 v131, v0
	v_mov_b32_e32 v132, v0
	v_mov_b32_e32 v133, v0
	v_mov_b32_e32 v134, v0
	v_mov_b32_e32 v135, v0
	v_mov_b32_e32 v112, v0
	v_mov_b32_e32 v113, v0
	v_mov_b32_e32 v114, v0
	v_mov_b32_e32 v115, v0
	v_mov_b32_e32 v116, v0
	v_mov_b32_e32 v117, v0
	v_mov_b32_e32 v118, v0
	v_mov_b32_e32 v119, v0
	v_mov_b32_e32 v72, v0
	v_mov_b32_e32 v73, v0
	v_mov_b32_e32 v74, v0
	v_mov_b32_e32 v75, v0
	v_mov_b32_e32 v76, v0
	v_mov_b32_e32 v77, v0
	v_mov_b32_e32 v78, v0
	v_mov_b32_e32 v79, v0
	v_mov_b32_e32 v96, v0
	v_mov_b32_e32 v97, v0
	v_mov_b32_e32 v98, v0
	v_mov_b32_e32 v99, v0
	v_mov_b32_e32 v100, v0
	v_mov_b32_e32 v101, v0
	v_mov_b32_e32 v102, v0
	v_mov_b32_e32 v103, v0
	v_mov_b32_e32 v144, v0
	v_mov_b32_e32 v145, v0
	v_mov_b32_e32 v146, v0
	v_mov_b32_e32 v147, v0
	v_mov_b32_e32 v156, v0
	v_mov_b32_e32 v157, v0
	v_mov_b32_e32 v158, v0
	v_mov_b32_e32 v159, v0
	v_mov_b32_e32 v120, v0
	v_mov_b32_e32 v121, v0
	v_mov_b32_e32 v122, v0
	v_mov_b32_e32 v123, v0
	v_mov_b32_e32 v124, v0
	v_mov_b32_e32 v125, v0
	v_mov_b32_e32 v126, v0
	v_mov_b32_e32 v127, v0
	v_add_u32_e32 v248, 0x18000, v233
	v_add_u32_e32 v249, 0x1c000, v233
.LBB0_836:
	ds_read_b128 v[88:91], v235
	ds_read_b128 v[92:95], v235 offset:1024
	ds_read_b128 v[104:107], v235 offset:2048
	ds_read_b128 v[108:111], v235 offset:3072
	ds_read_b128 v[136:139], v236
	ds_read_b128 v[140:143], v236 offset:1024
	ds_read_b128 v[148:151], v236 offset:2048
	ds_read_b128 v[152:155], v236 offset:3072
	s_add_u32 s42, s40, 0xfffc0080
	s_addc_u32 s43, s41, -1
	s_cmp_eq_u32 s63, 12
	s_cselect_b32 s45, s29, s43
	s_cselect_b32 s44, s37, s42
	s_cselect_b32 s43, s27, s62
	s_cselect_b32 s42, s39, s61
	s_add_i32 m0, s48, 0xc000
	ds_read_b128 v[160:163], v237
	ds_read_b128 v[164:167], v237 offset:1024
	ds_read_b128 v[168:171], v237 offset:2048
	ds_read_b128 v[172:175], v237 offset:3072
	ds_read_b128 v[176:179], v237 offset:4096
	ds_read_b128 v[180:183], v237 offset:5120
	ds_read_b128 v[184:187], v237 offset:6144
	ds_read_b128 v[188:191], v237 offset:7168
	global_load_lds_dwordx4 v200, s[40:41]
	s_add_i32 m0, s48, 0xe000
	s_nop 0
	global_load_lds_dwordx4 v202, s[40:41]
	s_waitcnt vmcnt(8)
	s_waitcnt lgkmcnt(0)
	s_barrier
	s_setprio 1
	s_waitcnt lgkmcnt(0)
	v_mfma_f32_16x16x32_bf16 v[124:127], v[88:91], v[160:163], v[124:127]
	v_mfma_f32_16x16x32_bf16 v[120:123], v[104:107], v[160:163], v[120:123]
	v_mfma_f32_16x16x32_bf16 v[156:159], v[88:91], v[168:171], v[156:159]
	v_mfma_f32_16x16x32_bf16 v[144:147], v[104:107], v[168:171], v[144:147]
	v_mfma_f32_16x16x32_bf16 v[100:103], v[88:91], v[176:179], v[100:103]
	v_mfma_f32_16x16x32_bf16 v[96:99], v[104:107], v[176:179], v[96:99]
	v_mfma_f32_16x16x32_bf16 v[76:79], v[88:91], v[184:187], v[76:79]
	v_mfma_f32_16x16x32_bf16 v[72:75], v[104:107], v[184:187], v[72:75]
	v_mfma_f32_16x16x32_bf16 v[124:127], v[92:95], v[164:167], v[124:127]
	v_mfma_f32_16x16x32_bf16 v[120:123], v[108:111], v[164:167], v[120:123]
	v_mfma_f32_16x16x32_bf16 v[156:159], v[92:95], v[172:175], v[156:159]
	v_mfma_f32_16x16x32_bf16 v[144:147], v[108:111], v[172:175], v[144:147]
	v_mfma_f32_16x16x32_bf16 v[100:103], v[92:95], v[180:183], v[100:103]
	v_mfma_f32_16x16x32_bf16 v[96:99], v[108:111], v[180:183], v[96:99]
	v_mfma_f32_16x16x32_bf16 v[76:79], v[92:95], v[188:191], v[76:79]
	v_mfma_f32_16x16x32_bf16 v[72:75], v[108:111], v[188:191], v[72:75]
	v_mfma_f32_16x16x32_bf16 v[116:119], v[136:139], v[160:163], v[116:119]
	v_mfma_f32_16x16x32_bf16 v[112:115], v[148:151], v[160:163], v[112:115]
	v_mfma_f32_16x16x32_bf16 v[132:135], v[136:139], v[168:171], v[132:135]
	v_mfma_f32_16x16x32_bf16 v[128:131], v[148:151], v[168:171], v[128:131]
	v_mfma_f32_16x16x32_bf16 v[84:87], v[136:139], v[176:179], v[84:87]
	v_mfma_f32_16x16x32_bf16 v[80:83], v[148:151], v[176:179], v[80:83]
	v_mfma_f32_16x16x32_bf16 v[68:71], v[136:139], v[184:187], v[68:71]
	v_mfma_f32_16x16x32_bf16 v[64:67], v[148:151], v[184:187], v[64:67]
	v_mfma_f32_16x16x32_bf16 v[116:119], v[140:143], v[164:167], v[116:119]
	v_mfma_f32_16x16x32_bf16 v[112:115], v[152:155], v[164:167], v[112:115]
	v_mfma_f32_16x16x32_bf16 v[132:135], v[140:143], v[172:175], v[132:135]
	v_mfma_f32_16x16x32_bf16 v[128:131], v[152:155], v[172:175], v[128:131]
	v_mfma_f32_16x16x32_bf16 v[84:87], v[140:143], v[180:183], v[84:87]
	v_mfma_f32_16x16x32_bf16 v[80:83], v[152:155], v[180:183], v[80:83]
	v_mfma_f32_16x16x32_bf16 v[68:71], v[140:143], v[188:191], v[68:71]
	v_mfma_f32_16x16x32_bf16 v[64:67], v[152:155], v[188:191], v[64:67]
	s_setprio 0
	s_barrier
	s_add_u32 s98, s42, s22
	s_addc_u32 s99, s43, s23
	s_add_u32 s100, s44, s22
	s_addc_u32 s101, s45, s23
	s_add_i32 s64, s59, s47
	s_mov_b32 m0, s64
	ds_read_b128 v[160:163], v237 offset:16384
	ds_read_b128 v[164:167], v237 offset:17408
	ds_read_b128 v[168:171], v237 offset:18432
	ds_read_b128 v[172:175], v237 offset:19456
	ds_read_b128 v[176:179], v237 offset:20480
	ds_read_b128 v[180:183], v237 offset:21504
	ds_read_b128 v[184:187], v237 offset:22528
	ds_read_b128 v[188:191], v237 offset:23552
	global_load_lds_dwordx4 v194, s[42:43]
	s_add_i32 m0, s64, 0x2000
	s_add_u32 s64, s42, 0x40000
	s_addc_u32 s65, s43, 0
	s_add_i32 s66, s60, s47
	global_load_lds_dwordx4 v198, s[42:43]
	s_mov_b32 m0, s66
	s_nop 0
	global_load_lds_dwordx4 v194, s[64:65]
	s_add_i32 m0, s66, 0x2000
	s_nop 0
	global_load_lds_dwordx4 v198, s[64:65]
	s_mov_b32 m0, s48
	s_nop 0
	global_load_lds_dwordx4 v192, s[44:45]
	s_mov_b32 m0, s49
	s_nop 0
	global_load_lds_dwordx4 v196, s[44:45]
	s_waitcnt vmcnt(8)
	s_waitcnt lgkmcnt(0)
	s_barrier
	s_setprio 1
	s_waitcnt lgkmcnt(0)
	v_mfma_f32_16x16x32_bf16 v[60:63], v[88:91], v[160:163], v[60:63]
	v_mfma_f32_16x16x32_bf16 v[56:59], v[104:107], v[160:163], v[56:59]
	v_mfma_f32_16x16x32_bf16 v[44:47], v[88:91], v[168:171], v[44:47]
	v_mfma_f32_16x16x32_bf16 v[40:43], v[104:107], v[168:171], v[40:43]
	v_mfma_f32_16x16x32_bf16 v[28:31], v[88:91], v[176:179], v[28:31]
	v_mfma_f32_16x16x32_bf16 v[24:27], v[104:107], v[176:179], v[24:27]
	v_mfma_f32_16x16x32_bf16 v[12:15], v[88:91], v[184:187], v[12:15]
	v_mfma_f32_16x16x32_bf16 v[8:11], v[104:107], v[184:187], v[8:11]
	v_mfma_f32_16x16x32_bf16 v[60:63], v[92:95], v[164:167], v[60:63]
	v_mfma_f32_16x16x32_bf16 v[56:59], v[108:111], v[164:167], v[56:59]
	v_mfma_f32_16x16x32_bf16 v[44:47], v[92:95], v[172:175], v[44:47]
	v_mfma_f32_16x16x32_bf16 v[40:43], v[108:111], v[172:175], v[40:43]
	v_mfma_f32_16x16x32_bf16 v[28:31], v[92:95], v[180:183], v[28:31]
	v_mfma_f32_16x16x32_bf16 v[24:27], v[108:111], v[180:183], v[24:27]
	v_mfma_f32_16x16x32_bf16 v[12:15], v[92:95], v[188:191], v[12:15]
	v_mfma_f32_16x16x32_bf16 v[8:11], v[108:111], v[188:191], v[8:11]
	v_mfma_f32_16x16x32_bf16 v[52:55], v[136:139], v[160:163], v[52:55]
	v_mfma_f32_16x16x32_bf16 v[48:51], v[148:151], v[160:163], v[48:51]
	v_mfma_f32_16x16x32_bf16 v[36:39], v[136:139], v[168:171], v[36:39]
	v_mfma_f32_16x16x32_bf16 v[32:35], v[148:151], v[168:171], v[32:35]
	v_mfma_f32_16x16x32_bf16 v[20:23], v[136:139], v[176:179], v[20:23]
	v_mfma_f32_16x16x32_bf16 v[16:19], v[148:151], v[176:179], v[16:19]
	v_mfma_f32_16x16x32_bf16 v[4:7], v[136:139], v[184:187], v[4:7]
	v_mfma_f32_16x16x32_bf16 v[0:3], v[148:151], v[184:187], v[0:3]
	v_mfma_f32_16x16x32_bf16 v[52:55], v[140:143], v[164:167], v[52:55]
	v_mfma_f32_16x16x32_bf16 v[48:51], v[152:155], v[164:167], v[48:51]
	v_mfma_f32_16x16x32_bf16 v[36:39], v[140:143], v[172:175], v[36:39]
	v_mfma_f32_16x16x32_bf16 v[32:35], v[152:155], v[172:175], v[32:35]
	v_mfma_f32_16x16x32_bf16 v[20:23], v[140:143], v[180:183], v[20:23]
	v_mfma_f32_16x16x32_bf16 v[16:19], v[152:155], v[180:183], v[16:19]
	v_mfma_f32_16x16x32_bf16 v[4:7], v[140:143], v[188:191], v[4:7]
	v_mfma_f32_16x16x32_bf16 v[0:3], v[152:155], v[188:191], v[0:3]
	s_setprio 0
	s_barrier
	s_add_i32 s64, 0, 0x18000
	s_add_i32 s65, 0, 0x1c000
	ds_read_b128 v[88:91], v248
	ds_read_b128 v[92:95], v248 offset:1024
	ds_read_b128 v[104:107], v248 offset:2048
	ds_read_b128 v[108:111], v248 offset:3072
	ds_read_b128 v[136:139], v249
	ds_read_b128 v[140:143], v249 offset:1024
	ds_read_b128 v[148:151], v249 offset:2048
	ds_read_b128 v[152:155], v249 offset:3072
	s_add_u32 s44, s44, 0x40000
	s_addc_u32 s45, s45, 0
	s_mov_b32 m0, s50
	ds_read_b128 v[160:163], v237 offset:32768
	ds_read_b128 v[164:167], v237 offset:33792
	ds_read_b128 v[168:171], v237 offset:34816
	ds_read_b128 v[172:175], v237 offset:35840
	ds_read_b128 v[176:179], v237 offset:36864
	ds_read_b128 v[180:183], v237 offset:37888
	ds_read_b128 v[184:187], v237 offset:38912
	ds_read_b128 v[188:191], v237 offset:39936
	global_load_lds_dwordx4 v192, s[44:45]
	s_mov_b32 m0, s51
	s_nop 0
	global_load_lds_dwordx4 v196, s[44:45]
	s_waitcnt vmcnt(8)
	s_waitcnt lgkmcnt(0)
	s_barrier
	s_setprio 1
	s_waitcnt lgkmcnt(0)
	v_mfma_f32_16x16x32_bf16 v[124:127], v[88:91], v[160:163], v[124:127]
	v_mfma_f32_16x16x32_bf16 v[120:123], v[104:107], v[160:163], v[120:123]
	v_mfma_f32_16x16x32_bf16 v[156:159], v[88:91], v[168:171], v[156:159]
	v_mfma_f32_16x16x32_bf16 v[144:147], v[104:107], v[168:171], v[144:147]
	v_mfma_f32_16x16x32_bf16 v[100:103], v[88:91], v[176:179], v[100:103]
	v_mfma_f32_16x16x32_bf16 v[96:99], v[104:107], v[176:179], v[96:99]
	v_mfma_f32_16x16x32_bf16 v[76:79], v[88:91], v[184:187], v[76:79]
	v_mfma_f32_16x16x32_bf16 v[72:75], v[104:107], v[184:187], v[72:75]
	v_mfma_f32_16x16x32_bf16 v[124:127], v[92:95], v[164:167], v[124:127]
	v_mfma_f32_16x16x32_bf16 v[120:123], v[108:111], v[164:167], v[120:123]
	v_mfma_f32_16x16x32_bf16 v[156:159], v[92:95], v[172:175], v[156:159]
	v_mfma_f32_16x16x32_bf16 v[144:147], v[108:111], v[172:175], v[144:147]
	v_mfma_f32_16x16x32_bf16 v[100:103], v[92:95], v[180:183], v[100:103]
	v_mfma_f32_16x16x32_bf16 v[96:99], v[108:111], v[180:183], v[96:99]
	v_mfma_f32_16x16x32_bf16 v[76:79], v[92:95], v[188:191], v[76:79]
	v_mfma_f32_16x16x32_bf16 v[72:75], v[108:111], v[188:191], v[72:75]
	v_mfma_f32_16x16x32_bf16 v[116:119], v[136:139], v[160:163], v[116:119]
	v_mfma_f32_16x16x32_bf16 v[112:115], v[148:151], v[160:163], v[112:115]
	v_mfma_f32_16x16x32_bf16 v[132:135], v[136:139], v[168:171], v[132:135]
	v_mfma_f32_16x16x32_bf16 v[128:131], v[148:151], v[168:171], v[128:131]
	v_mfma_f32_16x16x32_bf16 v[84:87], v[136:139], v[176:179], v[84:87]
	v_mfma_f32_16x16x32_bf16 v[80:83], v[148:151], v[176:179], v[80:83]
	v_mfma_f32_16x16x32_bf16 v[68:71], v[136:139], v[184:187], v[68:71]
	v_mfma_f32_16x16x32_bf16 v[64:67], v[148:151], v[184:187], v[64:67]
	v_mfma_f32_16x16x32_bf16 v[116:119], v[140:143], v[164:167], v[116:119]
	v_mfma_f32_16x16x32_bf16 v[112:115], v[152:155], v[164:167], v[112:115]
	v_mfma_f32_16x16x32_bf16 v[132:135], v[140:143], v[172:175], v[132:135]
	v_mfma_f32_16x16x32_bf16 v[128:131], v[152:155], v[172:175], v[128:131]
	v_mfma_f32_16x16x32_bf16 v[84:87], v[140:143], v[180:183], v[84:87]
	v_mfma_f32_16x16x32_bf16 v[80:83], v[152:155], v[180:183], v[80:83]
	v_mfma_f32_16x16x32_bf16 v[68:71], v[140:143], v[188:191], v[68:71]
	v_mfma_f32_16x16x32_bf16 v[64:67], v[152:155], v[188:191], v[64:67]
	s_setprio 0
	s_barrier
	s_add_i32 s44, s64, s47
	s_mov_b32 m0, s44
	ds_read_b128 v[160:163], v237 offset:49152
	ds_read_b128 v[164:167], v237 offset:50176
	ds_read_b128 v[168:171], v237 offset:51200
	ds_read_b128 v[172:175], v237 offset:52224
	ds_read_b128 v[176:179], v237 offset:53248
	ds_read_b128 v[180:183], v237 offset:54272
	ds_read_b128 v[184:187], v237 offset:55296
	ds_read_b128 v[188:191], v237 offset:56320
	global_load_lds_dwordx4 v194, s[98:99]
	s_add_i32 m0, s44, 0x2000
	s_add_u32 s42, s42, 0x40080
	s_addc_u32 s43, s43, 0
	s_add_i32 s44, s65, s47
	global_load_lds_dwordx4 v198, s[98:99]
	s_mov_b32 m0, s44
	s_nop 0
	global_load_lds_dwordx4 v194, s[42:43]
	s_add_i32 m0, s44, 0x2000
	s_nop 0
	global_load_lds_dwordx4 v198, s[42:43]
	s_mov_b32 m0, s55
	s_nop 0
	global_load_lds_dwordx4 v192, s[100:101]
	s_mov_b32 m0, s56
	s_nop 0
	global_load_lds_dwordx4 v196, s[100:101]
	s_waitcnt vmcnt(8)
	s_waitcnt lgkmcnt(0)
	s_barrier
	s_setprio 1
	s_waitcnt lgkmcnt(0)
	v_mfma_f32_16x16x32_bf16 v[60:63], v[88:91], v[160:163], v[60:63]
	v_mfma_f32_16x16x32_bf16 v[56:59], v[104:107], v[160:163], v[56:59]
	v_mfma_f32_16x16x32_bf16 v[44:47], v[88:91], v[168:171], v[44:47]
	v_mfma_f32_16x16x32_bf16 v[40:43], v[104:107], v[168:171], v[40:43]
	v_mfma_f32_16x16x32_bf16 v[28:31], v[88:91], v[176:179], v[28:31]
	v_mfma_f32_16x16x32_bf16 v[24:27], v[104:107], v[176:179], v[24:27]
	v_mfma_f32_16x16x32_bf16 v[12:15], v[88:91], v[184:187], v[12:15]
	v_mfma_f32_16x16x32_bf16 v[8:11], v[104:107], v[184:187], v[8:11]
	v_mfma_f32_16x16x32_bf16 v[60:63], v[92:95], v[164:167], v[60:63]
	v_mfma_f32_16x16x32_bf16 v[56:59], v[108:111], v[164:167], v[56:59]
	v_mfma_f32_16x16x32_bf16 v[44:47], v[92:95], v[172:175], v[44:47]
	v_mfma_f32_16x16x32_bf16 v[40:43], v[108:111], v[172:175], v[40:43]
	v_mfma_f32_16x16x32_bf16 v[28:31], v[92:95], v[180:183], v[28:31]
	v_mfma_f32_16x16x32_bf16 v[24:27], v[108:111], v[180:183], v[24:27]
	v_mfma_f32_16x16x32_bf16 v[12:15], v[92:95], v[188:191], v[12:15]
	v_mfma_f32_16x16x32_bf16 v[8:11], v[108:111], v[188:191], v[8:11]
	v_mfma_f32_16x16x32_bf16 v[52:55], v[136:139], v[160:163], v[52:55]
	v_mfma_f32_16x16x32_bf16 v[48:51], v[148:151], v[160:163], v[48:51]
	v_mfma_f32_16x16x32_bf16 v[36:39], v[136:139], v[168:171], v[36:39]
	v_mfma_f32_16x16x32_bf16 v[32:35], v[148:151], v[168:171], v[32:35]
	v_mfma_f32_16x16x32_bf16 v[20:23], v[136:139], v[176:179], v[20:23]
	v_mfma_f32_16x16x32_bf16 v[16:19], v[148:151], v[176:179], v[16:19]
	v_mfma_f32_16x16x32_bf16 v[4:7], v[136:139], v[184:187], v[4:7]
	v_mfma_f32_16x16x32_bf16 v[0:3], v[148:151], v[184:187], v[0:3]
	v_mfma_f32_16x16x32_bf16 v[52:55], v[140:143], v[164:167], v[52:55]
	v_mfma_f32_16x16x32_bf16 v[48:51], v[152:155], v[164:167], v[48:51]
	v_mfma_f32_16x16x32_bf16 v[36:39], v[140:143], v[172:175], v[36:39]
	v_mfma_f32_16x16x32_bf16 v[32:35], v[152:155], v[172:175], v[32:35]
	v_mfma_f32_16x16x32_bf16 v[20:23], v[140:143], v[180:183], v[20:23]
	v_mfma_f32_16x16x32_bf16 v[16:19], v[152:155], v[180:183], v[16:19]
	v_mfma_f32_16x16x32_bf16 v[4:7], v[140:143], v[188:191], v[4:7]
	v_mfma_f32_16x16x32_bf16 v[0:3], v[152:155], v[188:191], v[0:3]
	s_setprio 0
	s_barrier
	s_add_i32 s63, s63, 2
	s_add_u32 s40, s40, 0x100
	s_addc_u32 s41, s41, 0
	s_add_u32 s61, s61, 0x100
	s_addc_u32 s62, s62, 0
	s_cmp_gt_u32 s63, 13
	s_cbranch_scc0 .LBB0_836
	s_and_b64 vcc, exec, s[24:25]
	s_cbranch_vccz .LBB0_839
	s_barrier
